# G2: next branch's first K-step tiles prefetched by LDS-DMA into the idle LDS buffer during the gating stretch; loop top loads only for the first branch of a tile
# baseline (speedup 1.0000x reference)
; __device__ __forceinline__ int otid() { int t = threadIdx.x; asm volatile("" : "+v"(t)); return t; }
; template <bool DEEP>
; __device__ __forceinline__ void gemm_core(const bf16_t* __restrict__ A, int lda, const bf16_t* __restrict__ Bt, int ldb,
;                                           int K, f32x4 (&acc)[4][4], char* smem) {
;   bf16_t* sA = (bf16_t*)smem;
;   bf16_t* sB = sA + 2 * 128 * LDS_STRIDE;
;   const int tid = otid(), lane = tid & 63, wave = tid >> 6;
;   const int wm = wave >> 1, wn = wave & 1;
;   const int lr = tid >> 3, lc = (tid & 7) * 8;
;   const bf16_t* ap = A + (size_t)lr * lda + lc;
;   const bf16_t* bp = Bt + (size_t)lr * ldb + lc;
;   const int nk = K >> 6;
;   const int fr = lane & 15, fq = (lane >> 4) * 8;
;   const int rswz = (fr >> 1) & 7, wswz = (lr >> 1) & 7;
;   const int fo0 = (((lane >> 4)) ^ rswz) * 8, fo1 = ((4 + (lane >> 4)) ^ rswz) * 8;
;   const bf16_t* cA0 = sA + (wm * 64 + fr) * LDS_STRIDE;
;   const bf16_t* cB0 = sB + (wn * 64 + fr) * LDS_STRIDE;
;   bf16_t* wA = sA + lr * LDS_STRIDE + (((tid & 7) ^ wswz) * 8);
;   bf16_t* wB = sB + lr * LDS_STRIDE + (((tid & 7) ^ wswz) * 8);
;   constexpr int BUF = 128 * LDS_STRIDE;
;     ...
;   u32x4 ra0[4], rb0[4];
;   GLOAD(ra0, rb0, 0);
;   if (DEEP) {
;     u32x4 ra1[4], rb1[4];
;     GLOAD(ra1, rb1, 1);
;     __syncthreads();
;     SWRITE(ra0, rb0, 0);
;     __syncthreads();
;     for (int kt = 0; kt < nk; kt += 2) {
;       { const int k2 = min(kt + 2, nk - 1); GLOAD(ra0, rb0, k2); }
;       mma_ktile(cA0, cB0, fo0, fo1, acc);
;       SWRITE(ra1, rb1, 1);
;       __syncthreads();
;       { const int k3 = min(kt + 3, nk - 1); GLOAD(ra1, rb1, k3); }
;       mma_ktile(cA0 + BUF, cB0 + BUF, fo0, fo1, acc);
;       if (kt + 2 < nk) { SWRITE(ra0, rb0, 0); }
;       __syncthreads();
;     }
;   } else {
;     __syncthreads();
;     SWRITE(ra0, rb0, 0);
;     __syncthreads();
;     for (int kt = 0; kt < nk; ++kt) {
;       const int cur = kt & 1;
;       { const int k1 = min(kt + 1, nk - 1); GLOAD(ra0, rb0, k1); }
;       mma_ktile(cA0 + cur * BUF, cB0 + cur * BUF, fo0, fo1, acc);
;       if (kt + 1 < nk) { SWRITE(ra0, rb0, cur ^ 1); }
;       __syncthreads();
.LBB0_21:
	v_mov_b32_e32 v128, v178
	v_lshrrev_b32_e32 v177, 6, v178
	v_lshlrev_b32_e32 v177, 10, v177
	v_add_u32_e32 v177, 0x400, v177
	s_mov_b32 s29, 0x237f8000
	v_ashrrev_i32_e32 v126, 3, v128
	v_mad_i64_i32 v[4:5], s[30:31], v126, s78, 0
	v_lshrrev_b32_e32 v187, 4, v128
	v_xor_b32_e32 v187, v187, v128
	v_lshlrev_b32_e32 v6, 4, v187
	v_and_b32_e32 v6, 0x70, v6
	s_add_u32 s30, s13, s16
	v_ashrrev_i32_e32 v127, 31, v126
	v_or_b32_e32 v4, v4, v6
	s_addc_u32 s31, s28, s17
	v_lshl_add_u64 v[36:37], s[30:31], 0, v[4:5]
	v_lshlrev_b64 v[4:5], 10, v[126:127]
	s_add_u32 s30, s10, s14
	v_or_b32_e32 v4, v4, v6
	s_addc_u32 s31, s11, s15
	v_lshl_add_u64 v[32:33], s[30:31], 0, v[4:5]
	v_add_co_u32_e32 v38, vcc, s29, v32
	s_mov_b32 s29, 0x23800000
	s_nop 0
	v_addc_co_u32_e32 v39, vcc, 0, v33, vcc
	v_add_co_u32_e32 v40, vcc, s1, v36
	v_and_b32_e32 v4, 15, v128
	s_nop 0
	v_addc_co_u32_e32 v41, vcc, 0, v37, vcc
	v_add_co_u32_e32 v42, vcc, s29, v32
	v_lshrrev_b32_e32 v7, 1, v128
	s_nop 0
	v_addc_co_u32_e32 v43, vcc, 0, v33, vcc
	v_lshrrev_b32_e32 v5, 4, v128
	v_bfe_u32 v6, v128, 4, 2
	v_bfe_u32 v8, v128, 1, 3
	v_and_or_b32 v4, v7, s79, v4
	v_add_co_u32_e32 v44, vcc, s0, v36
	v_bitop3_b32 v127, v5, v8, 3 bitop3:0x6c
	v_bitop3_b32 v129, v6, v8, 4 bitop3:0x36
	v_lshlrev_b32_e32 v130, 7, v4
	v_xor_b32_e32 v131, v5, v128
	v_addc_co_u32_e32 v45, vcc, 0, v37, vcc
	s_mov_b32 s29, 0x23808000
	v_add_co_u32_e32 v46, vcc, s29, v32
	s_nop 0
	v_addc_co_u32_e32 v47, vcc, 0, v33, vcc
	s_mov_b32 s29, 0x48000
	v_add_co_u32_e32 v48, vcc, s29, v36
	s_nop 0
	v_addc_co_u32_e32 v49, vcc, 0, v37, vcc
	s_mov_b32 s29, 0x23810000
	v_add_co_u32_e32 v50, vcc, s29, v32
	s_nop 0
	v_addc_co_u32_e32 v51, vcc, 0, v33, vcc
	v_readfirstlane_b32 s29, v177
	s_cmp_lg_u32 s16, 0
	s_cbranch_scc1 .Lg2pf_skip
	s_mov_b32 m0, s29
	s_nop 0
	global_load_lds_dwordx4 v[36:37], off
	s_add_i32 m0, s29, 0x8000
	s_nop 0
	global_load_lds_dwordx4 v[38:39], off
	s_add_i32 m0, s29, 0x1000
	s_nop 0
	global_load_lds_dwordx4 v[40:41], off
	s_add_i32 m0, s29, 0x9000
	s_nop 0
	global_load_lds_dwordx4 v[42:43], off
	s_add_i32 m0, s29, 0x2000
	s_nop 0
	global_load_lds_dwordx4 v[44:45], off
	s_add_i32 m0, s29, 0xa000
	s_nop 0
	global_load_lds_dwordx4 v[46:47], off
	s_add_i32 m0, s29, 0x3000
	s_nop 0
	global_load_lds_dwordx4 v[48:49], off
	s_add_i32 m0, s29, 0xb000
	s_nop 0
	global_load_lds_dwordx4 v[50:51], off
.Lg2pf_skip:
	v_lshlrev_b32_e32 v131, 4, v131
	v_and_b32_e32 v131, 0x70, v131
	v_lshl_or_b32 v126, v126, 7, v131
	s_barrier
	s_add_u32 s30, s10, 0xcb20000
	s_addc_u32 s31, s11, 0
	v_lshlrev_b32_e32 v176, 4, v129
	v_or_b32_e32 v129, v130, v176
	v_add_u32_e32 v129, 0x400, v129
	s_add_u32 s16, s16, 0x400
	s_addc_u32 s17, s17, 0
	s_add_u32 s14, s14, 0x100000
	s_addc_u32 s15, s15, 0
	s_cmpk_eq_i32 s16, 0xc00
	s_waitcnt vmcnt(0)
	v_lshlrev_b32_e32 v4, 7, v128
	v_and_b32_e32 v131, 0x2780, v4
	s_waitcnt lgkmcnt(0)
	s_barrier
	s_add_i32 m0, s29, 0x3f80
	s_nop 0
	global_load_lds_dwordx4 v[36:37], off offset:128
	s_add_i32 m0, s29, 0xbf80
	s_nop 0
	global_load_lds_dwordx4 v[38:39], off offset:128
	s_add_i32 m0, s29, 0x4f80
	s_nop 0
	global_load_lds_dwordx4 v[40:41], off offset:128
	s_add_i32 m0, s29, 0xcf80
	s_nop 0
	global_load_lds_dwordx4 v[42:43], off offset:128
	s_add_i32 m0, s29, 0x5f80
	s_nop 0
	global_load_lds_dwordx4 v[44:45], off offset:128
	s_add_i32 m0, s29, 0xdf80
	s_nop 0
	global_load_lds_dwordx4 v[46:47], off offset:128
	s_add_i32 m0, s29, 0x6f80
	s_nop 0
	global_load_lds_dwordx4 v[48:49], off offset:128
	s_add_i32 m0, s29, 0xef80
	s_nop 0
	global_load_lds_dwordx4 v[50:51], off offset:128
	v_lshlrev_b32_e32 v128, 4, v127
	v_or_b32_e32 v127, v130, v128
	v_or_b32_e32 v128, v131, v128
	v_add_u32_e32 v127, 0x400, v127
	v_add_u32_e32 v128, 0x400, v128
	ds_read_b128 v[132:135], v127
	ds_read_b128 v[136:139], v127 offset:2048
	ds_read_b128 v[140:143], v127 offset:4096
	ds_read_b128 v[144:147], v127 offset:6144
	ds_read_b128 v[148:151], v128 offset:32768
	ds_read_b128 v[152:155], v128 offset:34816
	ds_read_b128 v[156:159], v128 offset:36864
	ds_read_b128 v[160:163], v128 offset:38912
	v_or_b32_e32 v130, v131, v176
	v_add_u32_e32 v130, 0x400, v130
	s_waitcnt lgkmcnt(3)
	v_mfma_f32_16x16x32_bf16 v[164:167], v[148:151], v[132:135], 0
	s_waitcnt lgkmcnt(2)
	v_mfma_f32_16x16x32_bf16 v[168:171], v[152:155], v[132:135], 0
	s_waitcnt lgkmcnt(1)
	v_mfma_f32_16x16x32_bf16 v[172:175], v[156:159], v[132:135], 0
	s_waitcnt lgkmcnt(0)
	v_mfma_f32_16x16x32_bf16 v[132:135], v[160:163], v[132:135], 0
	v_mfma_f32_16x16x32_bf16 v[188:191], v[148:151], v[136:139], 0
	v_mfma_f32_16x16x32_bf16 v[192:195], v[152:155], v[136:139], 0
	v_mfma_f32_16x16x32_bf16 v[196:199], v[156:159], v[136:139], 0
	v_mfma_f32_16x16x32_bf16 v[136:139], v[160:163], v[136:139], 0
	v_mfma_f32_16x16x32_bf16 v[200:203], v[148:151], v[140:143], 0
	v_mfma_f32_16x16x32_bf16 v[204:207], v[152:155], v[140:143], 0
	v_mfma_f32_16x16x32_bf16 v[208:211], v[156:159], v[140:143], 0
	v_mfma_f32_16x16x32_bf16 v[140:143], v[160:163], v[140:143], 0
	v_mfma_f32_16x16x32_bf16 v[148:151], v[148:151], v[144:147], 0
	v_mfma_f32_16x16x32_bf16 v[152:155], v[152:155], v[144:147], 0
	v_mfma_f32_16x16x32_bf16 v[156:159], v[156:159], v[144:147], 0
	v_mfma_f32_16x16x32_bf16 v[144:147], v[160:163], v[144:147], 0
	ds_read_b128 v[160:163], v129
	ds_read_b128 v[212:215], v129 offset:2048
	ds_read_b128 v[216:219], v129 offset:4096
	ds_read_b128 v[220:223], v129 offset:6144
	ds_read_b128 v[224:227], v130 offset:32768
	ds_read_b128 v[228:231], v130 offset:34816
	ds_read_b128 v[232:235], v130 offset:36864
	ds_read_b128 v[236:239], v130 offset:38912
	s_waitcnt vmcnt(0)
	s_waitcnt lgkmcnt(0)
	s_barrier
; #define GLOAD(RA, RB, kt_)                                                         \
;   _Pragma("unroll") for (int i = 0; i < 4; ++i) {                                  \
;     RA[i] = *(const u32x4*)(ap + (size_t)(32 * i) * lda + ((kt_) << 6));           \
;     RB[i] = *(const u32x4*)(bp + (size_t)(32 * i) * ldb + ((kt_) << 6));           \
;   }
; #define SWRITE(RA, RB, buf_)                                                       \
;   _Pragma("unroll") for (int i = 0; i < 4; ++i) {                                  \
;     *(u32x4*)(wA + (buf_) * BUF + 32 * i * LDS_STRIDE) = RA[i];                    \
;     *(u32x4*)(wB + (buf_) * BUF + 32 * i * LDS_STRIDE) = RB[i];                    \
;   }
; __device__ __forceinline__ void mma_ktile(const bf16_t* cA, const bf16_t* cB, int fo0, int fo1, f32x4 (&acc)[4][4]) {
; #pragma unroll
;   for (int ks = 0; ks < 2; ++ks) {
;     const int fo = ks ? fo1 : fo0;
;     bf16x8 af[4], bfr[4];
; #pragma unroll
;     for (int i = 0; i < 4; ++i) af[i] = *(const bf16x8*)(cA + i * 16 * LDS_STRIDE + fo);
; #pragma unroll
;     for (int j = 0; j < 4; ++j) bfr[j] = *(const bf16x8*)(cB + j * 16 * LDS_STRIDE + fo);
; #pragma unroll
;     for (int i = 0; i < 4; ++i)
; #pragma unroll
;       for (int j = 0; j < 4; ++j)
;         acc[i][j] = __builtin_amdgcn_mfma_f32_16x16x32_bf16(bfr[j], af[i], acc[i][j], 0, 0, 0);
;   }
; }
; template <bool DEEP>
; __device__ __forceinline__ void gemm_core(const bf16_t* __restrict__ A, int lda, const bf16_t* __restrict__ Bt, int ldb,
;                                           int K, f32x4 (&acc)[4][4], char* smem) {
;     ...
;     for (int kt = 0; kt < nk; ++kt) {
;       const int cur = kt & 1;
;       { const int k1 = min(kt + 1, nk - 1); GLOAD(ra0, rb0, k1); }
;       mma_ktile(cA0 + cur * BUF, cB0 + cur * BUF, fo0, fo1, acc);
;       if (kt + 1 < nk) { SWRITE(ra0, rb0, cur ^ 1); }
;       __syncthreads();
	s_add_i32 m0, s29, 0xffffff00
	s_nop 0
	global_load_lds_dwordx4 v[36:37], off offset:256
	s_add_i32 m0, s29, 0x7f00
	s_nop 0
	global_load_lds_dwordx4 v[38:39], off offset:256
	s_add_i32 m0, s29, 0xf00
	s_nop 0
	global_load_lds_dwordx4 v[40:41], off offset:256
	s_add_i32 m0, s29, 0x8f00
	s_nop 0
	global_load_lds_dwordx4 v[42:43], off offset:256
	s_add_i32 m0, s29, 0x1f00
	s_nop 0
	global_load_lds_dwordx4 v[44:45], off offset:256
	s_add_i32 m0, s29, 0x9f00
	s_nop 0
	global_load_lds_dwordx4 v[46:47], off offset:256
	s_add_i32 m0, s29, 0x2f00
	s_nop 0
	global_load_lds_dwordx4 v[48:49], off offset:256
	s_add_i32 m0, s29, 0xaf00
	s_nop 0
	global_load_lds_dwordx4 v[50:51], off offset:256
	v_mfma_f32_16x16x32_bf16 v[164:167], v[224:227], v[160:163], v[164:167]
	v_mfma_f32_16x16x32_bf16 v[168:171], v[228:231], v[160:163], v[168:171]
	v_mfma_f32_16x16x32_bf16 v[172:175], v[232:235], v[160:163], v[172:175]
	v_mfma_f32_16x16x32_bf16 v[132:135], v[236:239], v[160:163], v[132:135]
	v_mfma_f32_16x16x32_bf16 v[160:163], v[224:227], v[212:215], v[188:191]
	v_mfma_f32_16x16x32_bf16 v[188:191], v[228:231], v[212:215], v[192:195]
	v_mfma_f32_16x16x32_bf16 v[192:195], v[232:235], v[212:215], v[196:199]
	v_mfma_f32_16x16x32_bf16 v[136:139], v[236:239], v[212:215], v[136:139]
	v_mfma_f32_16x16x32_bf16 v[196:199], v[224:227], v[216:219], v[200:203]
	v_mfma_f32_16x16x32_bf16 v[200:203], v[228:231], v[216:219], v[204:207]
	v_mfma_f32_16x16x32_bf16 v[204:207], v[232:235], v[216:219], v[208:211]
	v_mfma_f32_16x16x32_bf16 v[140:143], v[236:239], v[216:219], v[140:143]
	v_mfma_f32_16x16x32_bf16 v[148:151], v[224:227], v[220:223], v[148:151]
	v_mfma_f32_16x16x32_bf16 v[152:155], v[228:231], v[220:223], v[152:155]
	v_mfma_f32_16x16x32_bf16 v[156:159], v[232:235], v[220:223], v[156:159]
	v_mfma_f32_16x16x32_bf16 v[144:147], v[236:239], v[220:223], v[144:147]
	ds_read_b128 v[208:211], v127 offset:16384
	ds_read_b128 v[212:215], v127 offset:18432
	ds_read_b128 v[216:219], v127 offset:20480
	ds_read_b128 v[220:223], v127 offset:22528
	ds_read_b128 v[224:227], v128 offset:49152
	ds_read_b128 v[228:231], v128 offset:51200
	ds_read_b128 v[232:235], v128 offset:53248
	ds_read_b128 v[236:239], v128 offset:55296
	s_waitcnt lgkmcnt(3)
	v_mfma_f32_16x16x32_bf16 v[164:167], v[224:227], v[208:211], v[164:167]
	s_waitcnt lgkmcnt(2)
	v_mfma_f32_16x16x32_bf16 v[168:171], v[228:231], v[208:211], v[168:171]
	s_waitcnt lgkmcnt(1)
	v_mfma_f32_16x16x32_bf16 v[172:175], v[232:235], v[208:211], v[172:175]
	s_waitcnt lgkmcnt(0)
	v_mfma_f32_16x16x32_bf16 v[132:135], v[236:239], v[208:211], v[132:135]
	v_mfma_f32_16x16x32_bf16 v[160:163], v[224:227], v[212:215], v[160:163]
	v_mfma_f32_16x16x32_bf16 v[188:191], v[228:231], v[212:215], v[188:191]
	v_mfma_f32_16x16x32_bf16 v[192:195], v[232:235], v[212:215], v[192:195]
	v_mfma_f32_16x16x32_bf16 v[136:139], v[236:239], v[212:215], v[136:139]
	v_mfma_f32_16x16x32_bf16 v[196:199], v[224:227], v[216:219], v[196:199]
	v_mfma_f32_16x16x32_bf16 v[200:203], v[228:231], v[216:219], v[200:203]
	v_mfma_f32_16x16x32_bf16 v[204:207], v[232:235], v[216:219], v[204:207]
	v_mfma_f32_16x16x32_bf16 v[140:143], v[236:239], v[216:219], v[140:143]
	v_mfma_f32_16x16x32_bf16 v[148:151], v[224:227], v[220:223], v[148:151]
	v_mfma_f32_16x16x32_bf16 v[152:155], v[228:231], v[220:223], v[152:155]
	v_mfma_f32_16x16x32_bf16 v[156:159], v[232:235], v[220:223], v[156:159]
	v_mfma_f32_16x16x32_bf16 v[144:147], v[236:239], v[220:223], v[144:147]
	ds_read_b128 v[208:211], v129 offset:16384
	ds_read_b128 v[212:215], v129 offset:18432
	ds_read_b128 v[216:219], v129 offset:20480
	ds_read_b128 v[220:223], v129 offset:22528
	ds_read_b128 v[224:227], v130 offset:49152
	ds_read_b128 v[228:231], v130 offset:51200
	ds_read_b128 v[232:235], v130 offset:53248
	ds_read_b128 v[236:239], v130 offset:55296
	s_waitcnt vmcnt(0)
	s_waitcnt lgkmcnt(0)
	s_barrier
	s_add_i32 m0, s29, 0x3e80
	s_nop 0
	global_load_lds_dwordx4 v[36:37], off offset:384
	s_add_i32 m0, s29, 0xbe80
	s_nop 0
	global_load_lds_dwordx4 v[38:39], off offset:384
	s_add_i32 m0, s29, 0x4e80
	s_nop 0
	global_load_lds_dwordx4 v[40:41], off offset:384
	s_add_i32 m0, s29, 0xce80
	s_nop 0
	global_load_lds_dwordx4 v[42:43], off offset:384
	s_add_i32 m0, s29, 0x5e80
	s_nop 0
	global_load_lds_dwordx4 v[44:45], off offset:384
	s_add_i32 m0, s29, 0xde80
	s_nop 0
	global_load_lds_dwordx4 v[46:47], off offset:384
	s_add_i32 m0, s29, 0x6e80
	s_nop 0
	global_load_lds_dwordx4 v[48:49], off offset:384
	s_add_i32 m0, s29, 0xee80
	s_nop 0
	global_load_lds_dwordx4 v[50:51], off offset:384
	v_mfma_f32_16x16x32_bf16 v[164:167], v[224:227], v[208:211], v[164:167]
	v_mfma_f32_16x16x32_bf16 v[168:171], v[228:231], v[208:211], v[168:171]
	v_mfma_f32_16x16x32_bf16 v[172:175], v[232:235], v[208:211], v[172:175]
	v_mfma_f32_16x16x32_bf16 v[132:135], v[236:239], v[208:211], v[132:135]
	v_mfma_f32_16x16x32_bf16 v[160:163], v[224:227], v[212:215], v[160:163]
	v_mfma_f32_16x16x32_bf16 v[188:191], v[228:231], v[212:215], v[188:191]
	v_mfma_f32_16x16x32_bf16 v[192:195], v[232:235], v[212:215], v[192:195]
	v_mfma_f32_16x16x32_bf16 v[136:139], v[236:239], v[212:215], v[136:139]
	v_mfma_f32_16x16x32_bf16 v[196:199], v[224:227], v[216:219], v[196:199]
	v_mfma_f32_16x16x32_bf16 v[200:203], v[228:231], v[216:219], v[200:203]
	v_mfma_f32_16x16x32_bf16 v[204:207], v[232:235], v[216:219], v[204:207]
	v_mfma_f32_16x16x32_bf16 v[140:143], v[236:239], v[216:219], v[140:143]
	v_mfma_f32_16x16x32_bf16 v[148:151], v[224:227], v[220:223], v[148:151]
	v_mfma_f32_16x16x32_bf16 v[152:155], v[228:231], v[220:223], v[152:155]
	v_mfma_f32_16x16x32_bf16 v[156:159], v[232:235], v[220:223], v[156:159]
	v_mfma_f32_16x16x32_bf16 v[144:147], v[236:239], v[220:223], v[144:147]
	ds_read_b128 v[208:211], v127
	ds_read_b128 v[212:215], v127 offset:2048
	ds_read_b128 v[216:219], v127 offset:4096
	ds_read_b128 v[220:223], v127 offset:6144
	ds_read_b128 v[224:227], v128 offset:32768
	ds_read_b128 v[228:231], v128 offset:34816
	ds_read_b128 v[232:235], v128 offset:36864
	ds_read_b128 v[236:239], v128 offset:38912
	s_waitcnt lgkmcnt(3)
; #define GLOAD(RA, RB, kt_)                                                         \
;   _Pragma("unroll") for (int i = 0; i < 4; ++i) {                                  \
;     RA[i] = *(const u32x4*)(ap + (size_t)(32 * i) * lda + ((kt_) << 6));           \
;     RB[i] = *(const u32x4*)(bp + (size_t)(32 * i) * ldb + ((kt_) << 6));           \
;   }
; #define SWRITE(RA, RB, buf_)                                                       \
;   _Pragma("unroll") for (int i = 0; i < 4; ++i) {                                  \
;     *(u32x4*)(wA + (buf_) * BUF + 32 * i * LDS_STRIDE) = RA[i];                    \
;     *(u32x4*)(wB + (buf_) * BUF + 32 * i * LDS_STRIDE) = RB[i];                    \
;   }
; __device__ __forceinline__ void mma_ktile(const bf16_t* cA, const bf16_t* cB, int fo0, int fo1, f32x4 (&acc)[4][4]) {
; #pragma unroll
;   for (int ks = 0; ks < 2; ++ks) {
;     const int fo = ks ? fo1 : fo0;
;     bf16x8 af[4], bfr[4];
; #pragma unroll
;     for (int i = 0; i < 4; ++i) af[i] = *(const bf16x8*)(cA + i * 16 * LDS_STRIDE + fo);
; #pragma unroll
;     for (int j = 0; j < 4; ++j) bfr[j] = *(const bf16x8*)(cB + j * 16 * LDS_STRIDE + fo);
; #pragma unroll
;     for (int i = 0; i < 4; ++i)
; #pragma unroll
;       for (int j = 0; j < 4; ++j)
;         acc[i][j] = __builtin_amdgcn_mfma_f32_16x16x32_bf16(bfr[j], af[i], acc[i][j], 0, 0, 0);
;   }
; }
; template <bool DEEP>
; __device__ __forceinline__ void gemm_core(const bf16_t* __restrict__ A, int lda, const bf16_t* __restrict__ Bt, int ldb,
;                                           int K, f32x4 (&acc)[4][4], char* smem) {
;     ...
;     for (int kt = 0; kt < nk; ++kt) {
;       const int cur = kt & 1;
;       { const int k1 = min(kt + 1, nk - 1); GLOAD(ra0, rb0, k1); }
;       mma_ktile(cA0 + cur * BUF, cB0 + cur * BUF, fo0, fo1, acc);
;       if (kt + 1 < nk) { SWRITE(ra0, rb0, cur ^ 1); }
;       __syncthreads();
	v_mfma_f32_16x16x32_bf16 v[164:167], v[224:227], v[208:211], v[164:167]
	s_waitcnt lgkmcnt(2)
	v_mfma_f32_16x16x32_bf16 v[168:171], v[228:231], v[208:211], v[168:171]
	s_waitcnt lgkmcnt(1)
	v_mfma_f32_16x16x32_bf16 v[172:175], v[232:235], v[208:211], v[172:175]
	s_waitcnt lgkmcnt(0)
	v_mfma_f32_16x16x32_bf16 v[132:135], v[236:239], v[208:211], v[132:135]
	v_mfma_f32_16x16x32_bf16 v[160:163], v[224:227], v[212:215], v[160:163]
	v_mfma_f32_16x16x32_bf16 v[188:191], v[228:231], v[212:215], v[188:191]
	v_mfma_f32_16x16x32_bf16 v[192:195], v[232:235], v[212:215], v[192:195]
	v_mfma_f32_16x16x32_bf16 v[136:139], v[236:239], v[212:215], v[136:139]
	v_mfma_f32_16x16x32_bf16 v[196:199], v[224:227], v[216:219], v[196:199]
	v_mfma_f32_16x16x32_bf16 v[200:203], v[228:231], v[216:219], v[200:203]
	v_mfma_f32_16x16x32_bf16 v[204:207], v[232:235], v[216:219], v[204:207]
	v_mfma_f32_16x16x32_bf16 v[140:143], v[236:239], v[216:219], v[140:143]
	v_mfma_f32_16x16x32_bf16 v[148:151], v[224:227], v[220:223], v[148:151]
	v_mfma_f32_16x16x32_bf16 v[152:155], v[228:231], v[220:223], v[152:155]
	v_mfma_f32_16x16x32_bf16 v[156:159], v[232:235], v[220:223], v[156:159]
	v_mfma_f32_16x16x32_bf16 v[144:147], v[236:239], v[220:223], v[144:147]
	ds_read_b128 v[208:211], v129
	ds_read_b128 v[212:215], v129 offset:2048
	ds_read_b128 v[216:219], v129 offset:4096
	ds_read_b128 v[220:223], v129 offset:6144
	ds_read_b128 v[224:227], v130 offset:32768
	ds_read_b128 v[228:231], v130 offset:34816
	ds_read_b128 v[232:235], v130 offset:36864
	ds_read_b128 v[236:239], v130 offset:38912
	s_waitcnt vmcnt(0)
	s_waitcnt lgkmcnt(0)
	s_barrier
	s_add_i32 m0, s29, 0xfffffe00
	s_nop 0
	global_load_lds_dwordx4 v[36:37], off offset:512
	s_add_i32 m0, s29, 0x7e00
	s_nop 0
	global_load_lds_dwordx4 v[38:39], off offset:512
	s_add_i32 m0, s29, 0xe00
	s_nop 0
	global_load_lds_dwordx4 v[40:41], off offset:512
	s_add_i32 m0, s29, 0x8e00
	s_nop 0
	global_load_lds_dwordx4 v[42:43], off offset:512
	s_add_i32 m0, s29, 0x1e00
	s_nop 0
	global_load_lds_dwordx4 v[44:45], off offset:512
	s_add_i32 m0, s29, 0x9e00
	s_nop 0
	global_load_lds_dwordx4 v[46:47], off offset:512
	s_add_i32 m0, s29, 0x2e00
	s_nop 0
	global_load_lds_dwordx4 v[48:49], off offset:512
	s_add_i32 m0, s29, 0xae00
	s_nop 0
	global_load_lds_dwordx4 v[50:51], off offset:512
	v_mfma_f32_16x16x32_bf16 v[164:167], v[224:227], v[208:211], v[164:167]
	v_mfma_f32_16x16x32_bf16 v[168:171], v[228:231], v[208:211], v[168:171]
	v_mfma_f32_16x16x32_bf16 v[172:175], v[232:235], v[208:211], v[172:175]
	v_mfma_f32_16x16x32_bf16 v[132:135], v[236:239], v[208:211], v[132:135]
	v_mfma_f32_16x16x32_bf16 v[160:163], v[224:227], v[212:215], v[160:163]
	v_mfma_f32_16x16x32_bf16 v[188:191], v[228:231], v[212:215], v[188:191]
	v_mfma_f32_16x16x32_bf16 v[192:195], v[232:235], v[212:215], v[192:195]
	v_mfma_f32_16x16x32_bf16 v[136:139], v[236:239], v[212:215], v[136:139]
	v_mfma_f32_16x16x32_bf16 v[196:199], v[224:227], v[216:219], v[196:199]
	v_mfma_f32_16x16x32_bf16 v[200:203], v[228:231], v[216:219], v[200:203]
	v_mfma_f32_16x16x32_bf16 v[204:207], v[232:235], v[216:219], v[204:207]
	v_mfma_f32_16x16x32_bf16 v[140:143], v[236:239], v[216:219], v[140:143]
	v_mfma_f32_16x16x32_bf16 v[148:151], v[224:227], v[220:223], v[148:151]
	v_mfma_f32_16x16x32_bf16 v[152:155], v[228:231], v[220:223], v[152:155]
	v_mfma_f32_16x16x32_bf16 v[156:159], v[232:235], v[220:223], v[156:159]
	v_mfma_f32_16x16x32_bf16 v[144:147], v[236:239], v[220:223], v[144:147]
	ds_read_b128 v[208:211], v127 offset:16384
	ds_read_b128 v[212:215], v127 offset:18432
	ds_read_b128 v[216:219], v127 offset:20480
	ds_read_b128 v[220:223], v127 offset:22528
	ds_read_b128 v[224:227], v128 offset:49152
	ds_read_b128 v[228:231], v128 offset:51200
	ds_read_b128 v[232:235], v128 offset:53248
	ds_read_b128 v[236:239], v128 offset:55296
	s_waitcnt lgkmcnt(3)
	v_mfma_f32_16x16x32_bf16 v[164:167], v[224:227], v[208:211], v[164:167]
	s_waitcnt lgkmcnt(2)
	v_mfma_f32_16x16x32_bf16 v[168:171], v[228:231], v[208:211], v[168:171]
	s_waitcnt lgkmcnt(1)
	v_mfma_f32_16x16x32_bf16 v[172:175], v[232:235], v[208:211], v[172:175]
	s_waitcnt lgkmcnt(0)
	v_mfma_f32_16x16x32_bf16 v[132:135], v[236:239], v[208:211], v[132:135]
	v_mfma_f32_16x16x32_bf16 v[160:163], v[224:227], v[212:215], v[160:163]
	v_mfma_f32_16x16x32_bf16 v[188:191], v[228:231], v[212:215], v[188:191]
	v_mfma_f32_16x16x32_bf16 v[192:195], v[232:235], v[212:215], v[192:195]
	v_mfma_f32_16x16x32_bf16 v[136:139], v[236:239], v[212:215], v[136:139]
	v_mfma_f32_16x16x32_bf16 v[196:199], v[224:227], v[216:219], v[196:199]
	v_mfma_f32_16x16x32_bf16 v[200:203], v[228:231], v[216:219], v[200:203]
	v_mfma_f32_16x16x32_bf16 v[204:207], v[232:235], v[216:219], v[204:207]
	v_mfma_f32_16x16x32_bf16 v[140:143], v[236:239], v[216:219], v[140:143]
	v_mfma_f32_16x16x32_bf16 v[148:151], v[224:227], v[220:223], v[148:151]
	v_mfma_f32_16x16x32_bf16 v[152:155], v[228:231], v[220:223], v[152:155]
	v_mfma_f32_16x16x32_bf16 v[156:159], v[232:235], v[220:223], v[156:159]
	v_mfma_f32_16x16x32_bf16 v[144:147], v[236:239], v[220:223], v[144:147]
	ds_read_b128 v[208:211], v129 offset:16384
	ds_read_b128 v[212:215], v129 offset:18432
	ds_read_b128 v[216:219], v129 offset:20480
	ds_read_b128 v[220:223], v129 offset:22528
	ds_read_b128 v[224:227], v130 offset:49152
	ds_read_b128 v[228:231], v130 offset:51200
	ds_read_b128 v[232:235], v130 offset:53248
	ds_read_b128 v[236:239], v130 offset:55296
	s_waitcnt vmcnt(0)
	s_waitcnt lgkmcnt(0)
	s_barrier
; #define GLOAD(RA, RB, kt_)                                                         \
;   _Pragma("unroll") for (int i = 0; i < 4; ++i) {                                  \
;     RA[i] = *(const u32x4*)(ap + (size_t)(32 * i) * lda + ((kt_) << 6));           \
;     RB[i] = *(const u32x4*)(bp + (size_t)(32 * i) * ldb + ((kt_) << 6));           \
;   }
; #define SWRITE(RA, RB, buf_)                                                       \
;   _Pragma("unroll") for (int i = 0; i < 4; ++i) {                                  \
;     *(u32x4*)(wA + (buf_) * BUF + 32 * i * LDS_STRIDE) = RA[i];                    \
;     *(u32x4*)(wB + (buf_) * BUF + 32 * i * LDS_STRIDE) = RB[i];                    \
;   }
; __device__ __forceinline__ void mma_ktile(const bf16_t* cA, const bf16_t* cB, int fo0, int fo1, f32x4 (&acc)[4][4]) {
; #pragma unroll
;   for (int ks = 0; ks < 2; ++ks) {
;     const int fo = ks ? fo1 : fo0;
;     bf16x8 af[4], bfr[4];
; #pragma unroll
;     for (int i = 0; i < 4; ++i) af[i] = *(const bf16x8*)(cA + i * 16 * LDS_STRIDE + fo);
; #pragma unroll
;     for (int j = 0; j < 4; ++j) bfr[j] = *(const bf16x8*)(cB + j * 16 * LDS_STRIDE + fo);
; #pragma unroll
;     for (int i = 0; i < 4; ++i)
; #pragma unroll
;       for (int j = 0; j < 4; ++j)
;         acc[i][j] = __builtin_amdgcn_mfma_f32_16x16x32_bf16(bfr[j], af[i], acc[i][j], 0, 0, 0);
;   }
; }
; template <bool DEEP>
; __device__ __forceinline__ void gemm_core(const bf16_t* __restrict__ A, int lda, const bf16_t* __restrict__ Bt, int ldb,
;                                           int K, f32x4 (&acc)[4][4], char* smem) {
;     ...
;     for (int kt = 0; kt < nk; ++kt) {
;       const int cur = kt & 1;
;       { const int k1 = min(kt + 1, nk - 1); GLOAD(ra0, rb0, k1); }
;       mma_ktile(cA0 + cur * BUF, cB0 + cur * BUF, fo0, fo1, acc);
;       if (kt + 1 < nk) { SWRITE(ra0, rb0, cur ^ 1); }
;       __syncthreads();
	s_add_i32 m0, s29, 0x3d80
	s_nop 0
	global_load_lds_dwordx4 v[36:37], off offset:640
	s_add_i32 m0, s29, 0xbd80
	s_nop 0
	global_load_lds_dwordx4 v[38:39], off offset:640
	s_add_i32 m0, s29, 0x4d80
	s_nop 0
	global_load_lds_dwordx4 v[40:41], off offset:640
	s_add_i32 m0, s29, 0xcd80
	s_nop 0
	global_load_lds_dwordx4 v[42:43], off offset:640
	s_add_i32 m0, s29, 0x5d80
	s_nop 0
	global_load_lds_dwordx4 v[44:45], off offset:640
	s_add_i32 m0, s29, 0xdd80
	s_nop 0
	global_load_lds_dwordx4 v[46:47], off offset:640
	s_add_i32 m0, s29, 0x6d80
	s_nop 0
	global_load_lds_dwordx4 v[48:49], off offset:640
	s_add_i32 m0, s29, 0xed80
	s_nop 0
	global_load_lds_dwordx4 v[50:51], off offset:640
	v_mfma_f32_16x16x32_bf16 v[164:167], v[224:227], v[208:211], v[164:167]
	v_mfma_f32_16x16x32_bf16 v[168:171], v[228:231], v[208:211], v[168:171]
	v_mfma_f32_16x16x32_bf16 v[172:175], v[232:235], v[208:211], v[172:175]
	v_mfma_f32_16x16x32_bf16 v[132:135], v[236:239], v[208:211], v[132:135]
	v_mfma_f32_16x16x32_bf16 v[160:163], v[224:227], v[212:215], v[160:163]
	v_mfma_f32_16x16x32_bf16 v[188:191], v[228:231], v[212:215], v[188:191]
	v_mfma_f32_16x16x32_bf16 v[192:195], v[232:235], v[212:215], v[192:195]
	v_mfma_f32_16x16x32_bf16 v[136:139], v[236:239], v[212:215], v[136:139]
	v_mfma_f32_16x16x32_bf16 v[196:199], v[224:227], v[216:219], v[196:199]
	v_mfma_f32_16x16x32_bf16 v[200:203], v[228:231], v[216:219], v[200:203]
	v_mfma_f32_16x16x32_bf16 v[204:207], v[232:235], v[216:219], v[204:207]
	v_mfma_f32_16x16x32_bf16 v[140:143], v[236:239], v[216:219], v[140:143]
	v_mfma_f32_16x16x32_bf16 v[148:151], v[224:227], v[220:223], v[148:151]
	v_mfma_f32_16x16x32_bf16 v[152:155], v[228:231], v[220:223], v[152:155]
	v_mfma_f32_16x16x32_bf16 v[156:159], v[232:235], v[220:223], v[156:159]
	v_mfma_f32_16x16x32_bf16 v[144:147], v[236:239], v[220:223], v[144:147]
	ds_read_b128 v[208:211], v127
	ds_read_b128 v[212:215], v127 offset:2048
	ds_read_b128 v[216:219], v127 offset:4096
	ds_read_b128 v[220:223], v127 offset:6144
	ds_read_b128 v[224:227], v128 offset:32768
	ds_read_b128 v[228:231], v128 offset:34816
	ds_read_b128 v[232:235], v128 offset:36864
	ds_read_b128 v[236:239], v128 offset:38912
	s_waitcnt lgkmcnt(3)
	v_mfma_f32_16x16x32_bf16 v[164:167], v[224:227], v[208:211], v[164:167]
	s_waitcnt lgkmcnt(2)
	v_mfma_f32_16x16x32_bf16 v[168:171], v[228:231], v[208:211], v[168:171]
	s_waitcnt lgkmcnt(1)
	v_mfma_f32_16x16x32_bf16 v[172:175], v[232:235], v[208:211], v[172:175]
	s_waitcnt lgkmcnt(0)
	v_mfma_f32_16x16x32_bf16 v[132:135], v[236:239], v[208:211], v[132:135]
	v_mfma_f32_16x16x32_bf16 v[160:163], v[224:227], v[212:215], v[160:163]
	v_mfma_f32_16x16x32_bf16 v[188:191], v[228:231], v[212:215], v[188:191]
	v_mfma_f32_16x16x32_bf16 v[192:195], v[232:235], v[212:215], v[192:195]
	v_mfma_f32_16x16x32_bf16 v[136:139], v[236:239], v[212:215], v[136:139]
	v_mfma_f32_16x16x32_bf16 v[196:199], v[224:227], v[216:219], v[196:199]
	v_mfma_f32_16x16x32_bf16 v[200:203], v[228:231], v[216:219], v[200:203]
	v_mfma_f32_16x16x32_bf16 v[204:207], v[232:235], v[216:219], v[204:207]
	v_mfma_f32_16x16x32_bf16 v[140:143], v[236:239], v[216:219], v[140:143]
	v_mfma_f32_16x16x32_bf16 v[148:151], v[224:227], v[220:223], v[148:151]
	v_mfma_f32_16x16x32_bf16 v[152:155], v[228:231], v[220:223], v[152:155]
	v_mfma_f32_16x16x32_bf16 v[156:159], v[232:235], v[220:223], v[156:159]
	v_mfma_f32_16x16x32_bf16 v[144:147], v[236:239], v[220:223], v[144:147]
	ds_read_b128 v[208:211], v129
	ds_read_b128 v[212:215], v129 offset:2048
	ds_read_b128 v[216:219], v129 offset:4096
	ds_read_b128 v[220:223], v129 offset:6144
	ds_read_b128 v[224:227], v130 offset:32768
	ds_read_b128 v[228:231], v130 offset:34816
	ds_read_b128 v[232:235], v130 offset:36864
	ds_read_b128 v[236:239], v130 offset:38912
	s_waitcnt vmcnt(0)
	s_waitcnt lgkmcnt(0)
	s_barrier
	s_add_i32 m0, s29, 0xfffffd00
	s_nop 0
	global_load_lds_dwordx4 v[36:37], off offset:768
	s_add_i32 m0, s29, 0x7d00
	s_nop 0
	global_load_lds_dwordx4 v[38:39], off offset:768
	s_add_i32 m0, s29, 0xd00
	s_nop 0
	global_load_lds_dwordx4 v[40:41], off offset:768
	s_add_i32 m0, s29, 0x8d00
	s_nop 0
	global_load_lds_dwordx4 v[42:43], off offset:768
	s_add_i32 m0, s29, 0x1d00
	s_nop 0
	global_load_lds_dwordx4 v[44:45], off offset:768
	s_add_i32 m0, s29, 0x9d00
	s_nop 0
	global_load_lds_dwordx4 v[46:47], off offset:768
	s_add_i32 m0, s29, 0x2d00
	s_nop 0
	global_load_lds_dwordx4 v[48:49], off offset:768
	s_add_i32 m0, s29, 0xad00
	s_nop 0
	global_load_lds_dwordx4 v[50:51], off offset:768
	v_mfma_f32_16x16x32_bf16 v[164:167], v[224:227], v[208:211], v[164:167]
	v_mfma_f32_16x16x32_bf16 v[168:171], v[228:231], v[208:211], v[168:171]
	v_mfma_f32_16x16x32_bf16 v[172:175], v[232:235], v[208:211], v[172:175]
	v_mfma_f32_16x16x32_bf16 v[132:135], v[236:239], v[208:211], v[132:135]
	v_mfma_f32_16x16x32_bf16 v[160:163], v[224:227], v[212:215], v[160:163]
	v_mfma_f32_16x16x32_bf16 v[188:191], v[228:231], v[212:215], v[188:191]
	v_mfma_f32_16x16x32_bf16 v[192:195], v[232:235], v[212:215], v[192:195]
	v_mfma_f32_16x16x32_bf16 v[136:139], v[236:239], v[212:215], v[136:139]
	v_mfma_f32_16x16x32_bf16 v[196:199], v[224:227], v[216:219], v[196:199]
	v_mfma_f32_16x16x32_bf16 v[200:203], v[228:231], v[216:219], v[200:203]
	v_mfma_f32_16x16x32_bf16 v[204:207], v[232:235], v[216:219], v[204:207]
	v_mfma_f32_16x16x32_bf16 v[140:143], v[236:239], v[216:219], v[140:143]
	v_mfma_f32_16x16x32_bf16 v[148:151], v[224:227], v[220:223], v[148:151]
	v_mfma_f32_16x16x32_bf16 v[152:155], v[228:231], v[220:223], v[152:155]
	v_mfma_f32_16x16x32_bf16 v[156:159], v[232:235], v[220:223], v[156:159]
	v_mfma_f32_16x16x32_bf16 v[144:147], v[236:239], v[220:223], v[144:147]
	ds_read_b128 v[208:211], v127 offset:16384
	ds_read_b128 v[212:215], v127 offset:18432
	ds_read_b128 v[216:219], v127 offset:20480
	ds_read_b128 v[220:223], v127 offset:22528
	ds_read_b128 v[224:227], v128 offset:49152
	ds_read_b128 v[228:231], v128 offset:51200
	ds_read_b128 v[232:235], v128 offset:53248
	ds_read_b128 v[236:239], v128 offset:55296
	s_waitcnt lgkmcnt(3)
; #define GLOAD(RA, RB, kt_)                                                         \
;   _Pragma("unroll") for (int i = 0; i < 4; ++i) {                                  \
;     RA[i] = *(const u32x4*)(ap + (size_t)(32 * i) * lda + ((kt_) << 6));           \
;     RB[i] = *(const u32x4*)(bp + (size_t)(32 * i) * ldb + ((kt_) << 6));           \
;   }
; #define SWRITE(RA, RB, buf_)                                                       \
;   _Pragma("unroll") for (int i = 0; i < 4; ++i) {                                  \
;     *(u32x4*)(wA + (buf_) * BUF + 32 * i * LDS_STRIDE) = RA[i];                    \
;     *(u32x4*)(wB + (buf_) * BUF + 32 * i * LDS_STRIDE) = RB[i];                    \
;   }
; __device__ __forceinline__ void mma_ktile(const bf16_t* cA, const bf16_t* cB, int fo0, int fo1, f32x4 (&acc)[4][4]) {
; #pragma unroll
;   for (int ks = 0; ks < 2; ++ks) {
;     const int fo = ks ? fo1 : fo0;
;     bf16x8 af[4], bfr[4];
; #pragma unroll
;     for (int i = 0; i < 4; ++i) af[i] = *(const bf16x8*)(cA + i * 16 * LDS_STRIDE + fo);
; #pragma unroll
;     for (int j = 0; j < 4; ++j) bfr[j] = *(const bf16x8*)(cB + j * 16 * LDS_STRIDE + fo);
; #pragma unroll
;     for (int i = 0; i < 4; ++i)
; #pragma unroll
;       for (int j = 0; j < 4; ++j)
;         acc[i][j] = __builtin_amdgcn_mfma_f32_16x16x32_bf16(bfr[j], af[i], acc[i][j], 0, 0, 0);
;   }
; }
; template <bool DEEP>
; __device__ __forceinline__ void gemm_core(const bf16_t* __restrict__ A, int lda, const bf16_t* __restrict__ Bt, int ldb,
;                                           int K, f32x4 (&acc)[4][4], char* smem) {
;     ...
;     for (int kt = 0; kt < nk; ++kt) {
;       const int cur = kt & 1;
;       { const int k1 = min(kt + 1, nk - 1); GLOAD(ra0, rb0, k1); }
;       mma_ktile(cA0 + cur * BUF, cB0 + cur * BUF, fo0, fo1, acc);
;       if (kt + 1 < nk) { SWRITE(ra0, rb0, cur ^ 1); }
;       __syncthreads();
	v_mfma_f32_16x16x32_bf16 v[164:167], v[224:227], v[208:211], v[164:167]
	s_waitcnt lgkmcnt(2)
	v_mfma_f32_16x16x32_bf16 v[168:171], v[228:231], v[208:211], v[168:171]
	s_waitcnt lgkmcnt(1)
	v_mfma_f32_16x16x32_bf16 v[172:175], v[232:235], v[208:211], v[172:175]
	s_waitcnt lgkmcnt(0)
	v_mfma_f32_16x16x32_bf16 v[132:135], v[236:239], v[208:211], v[132:135]
	v_mfma_f32_16x16x32_bf16 v[160:163], v[224:227], v[212:215], v[160:163]
	v_mfma_f32_16x16x32_bf16 v[188:191], v[228:231], v[212:215], v[188:191]
	v_mfma_f32_16x16x32_bf16 v[192:195], v[232:235], v[212:215], v[192:195]
	v_mfma_f32_16x16x32_bf16 v[136:139], v[236:239], v[212:215], v[136:139]
	v_mfma_f32_16x16x32_bf16 v[196:199], v[224:227], v[216:219], v[196:199]
	v_mfma_f32_16x16x32_bf16 v[200:203], v[228:231], v[216:219], v[200:203]
	v_mfma_f32_16x16x32_bf16 v[204:207], v[232:235], v[216:219], v[204:207]
	v_mfma_f32_16x16x32_bf16 v[140:143], v[236:239], v[216:219], v[140:143]
	v_mfma_f32_16x16x32_bf16 v[148:151], v[224:227], v[220:223], v[148:151]
	v_mfma_f32_16x16x32_bf16 v[152:155], v[228:231], v[220:223], v[152:155]
	v_mfma_f32_16x16x32_bf16 v[156:159], v[232:235], v[220:223], v[156:159]
	v_mfma_f32_16x16x32_bf16 v[144:147], v[236:239], v[220:223], v[144:147]
	ds_read_b128 v[208:211], v129 offset:16384
	ds_read_b128 v[212:215], v129 offset:18432
	ds_read_b128 v[216:219], v129 offset:20480
	ds_read_b128 v[220:223], v129 offset:22528
	ds_read_b128 v[224:227], v130 offset:49152
	ds_read_b128 v[228:231], v130 offset:51200
	ds_read_b128 v[232:235], v130 offset:53248
	ds_read_b128 v[236:239], v130 offset:55296
	s_waitcnt vmcnt(0)
	s_waitcnt lgkmcnt(0)
	s_barrier
	s_add_i32 m0, s29, 0x3c80
	s_nop 0
	global_load_lds_dwordx4 v[36:37], off offset:896
	s_add_i32 m0, s29, 0xbc80
	s_nop 0
	global_load_lds_dwordx4 v[38:39], off offset:896
	s_add_i32 m0, s29, 0x4c80
	s_nop 0
	global_load_lds_dwordx4 v[40:41], off offset:896
	s_add_i32 m0, s29, 0xcc80
	s_nop 0
	global_load_lds_dwordx4 v[42:43], off offset:896
	s_add_i32 m0, s29, 0x5c80
	s_nop 0
	global_load_lds_dwordx4 v[44:45], off offset:896
	s_add_i32 m0, s29, 0xdc80
	s_nop 0
	global_load_lds_dwordx4 v[46:47], off offset:896
	s_add_i32 m0, s29, 0x6c80
	s_nop 0
	global_load_lds_dwordx4 v[48:49], off offset:896
	s_add_i32 m0, s29, 0xec80
	s_nop 0
	global_load_lds_dwordx4 v[50:51], off offset:896
	v_mfma_f32_16x16x32_bf16 v[164:167], v[224:227], v[208:211], v[164:167]
	v_mfma_f32_16x16x32_bf16 v[168:171], v[228:231], v[208:211], v[168:171]
	v_mfma_f32_16x16x32_bf16 v[172:175], v[232:235], v[208:211], v[172:175]
	v_mfma_f32_16x16x32_bf16 v[132:135], v[236:239], v[208:211], v[132:135]
	v_mfma_f32_16x16x32_bf16 v[160:163], v[224:227], v[212:215], v[160:163]
	v_mfma_f32_16x16x32_bf16 v[188:191], v[228:231], v[212:215], v[188:191]
	v_mfma_f32_16x16x32_bf16 v[192:195], v[232:235], v[212:215], v[192:195]
	v_mfma_f32_16x16x32_bf16 v[136:139], v[236:239], v[212:215], v[136:139]
	v_mfma_f32_16x16x32_bf16 v[196:199], v[224:227], v[216:219], v[196:199]
	v_mfma_f32_16x16x32_bf16 v[200:203], v[228:231], v[216:219], v[200:203]
	v_mfma_f32_16x16x32_bf16 v[204:207], v[232:235], v[216:219], v[204:207]
	v_mfma_f32_16x16x32_bf16 v[140:143], v[236:239], v[216:219], v[140:143]
	v_mfma_f32_16x16x32_bf16 v[148:151], v[224:227], v[220:223], v[148:151]
	v_mfma_f32_16x16x32_bf16 v[152:155], v[228:231], v[220:223], v[152:155]
	v_mfma_f32_16x16x32_bf16 v[156:159], v[232:235], v[220:223], v[156:159]
	v_mfma_f32_16x16x32_bf16 v[144:147], v[236:239], v[220:223], v[144:147]
	global_load_dwordx2 v[224:225], v110, s[30:31] offset:3072
	global_load_dwordx2 v[226:227], v110, s[30:31] offset:3104
	global_load_dwordx2 v[228:229], v110, s[30:31] offset:3136
	global_load_dwordx2 v[230:231], v110, s[30:31] offset:3168
	global_load_dwordx2 v[232:233], v106, s[30:31] offset:3072
	global_load_dwordx2 v[234:235], v106, s[30:31] offset:3104
	global_load_dwordx2 v[236:237], v106, s[30:31] offset:3136
	global_load_dwordx2 v[238:239], v106, s[30:31] offset:3168
	ds_read_b128 v[36:39], v127
	ds_read_b128 v[40:43], v127 offset:2048
	ds_read_b128 v[44:47], v127 offset:4096
	ds_read_b128 v[48:51], v127 offset:6144
	ds_read_b128 v[208:211], v128 offset:32768
	ds_read_b128 v[212:215], v128 offset:34816
	ds_read_b128 v[216:219], v128 offset:36864
	ds_read_b128 v[220:223], v128 offset:38912
	s_waitcnt lgkmcnt(3)
	v_mfma_f32_16x16x32_bf16 v[164:167], v[208:211], v[36:39], v[164:167]
	s_waitcnt lgkmcnt(2)
	v_mfma_f32_16x16x32_bf16 v[168:171], v[212:215], v[36:39], v[168:171]
	s_waitcnt lgkmcnt(1)
	v_mfma_f32_16x16x32_bf16 v[172:175], v[216:219], v[36:39], v[172:175]
	s_waitcnt lgkmcnt(0)
	v_mfma_f32_16x16x32_bf16 v[36:39], v[220:223], v[36:39], v[132:135]
	v_mfma_f32_16x16x32_bf16 v[132:135], v[208:211], v[40:43], v[160:163]
	v_mfma_f32_16x16x32_bf16 v[160:163], v[212:215], v[40:43], v[188:191]
	v_mfma_f32_16x16x32_bf16 v[188:191], v[216:219], v[40:43], v[192:195]
	v_mfma_f32_16x16x32_bf16 v[40:43], v[220:223], v[40:43], v[136:139]
	v_mfma_f32_16x16x32_bf16 v[136:139], v[208:211], v[44:47], v[196:199]
	v_mfma_f32_16x16x32_bf16 v[192:195], v[212:215], v[44:47], v[200:203]
	v_mfma_f32_16x16x32_bf16 v[196:199], v[216:219], v[44:47], v[204:207]
	v_mfma_f32_16x16x32_bf16 v[44:47], v[220:223], v[44:47], v[140:143]
	v_mfma_f32_16x16x32_bf16 v[140:143], v[208:211], v[48:51], v[148:151]
	v_mfma_f32_16x16x32_bf16 v[148:151], v[212:215], v[48:51], v[152:155]
	v_mfma_f32_16x16x32_bf16 v[152:155], v[216:219], v[48:51], v[156:159]
	v_mfma_f32_16x16x32_bf16 v[48:51], v[220:223], v[48:51], v[144:147]
	s_nop 2
	ds_read_b128 v[144:147], v129
	ds_read_b128 v[156:159], v129 offset:2048
	ds_read_b128 v[200:203], v129 offset:4096
	ds_read_b128 v[204:207], v129 offset:6144
	ds_read_b128 v[208:211], v130 offset:32768
	ds_read_b128 v[212:215], v130 offset:34816
	ds_read_b128 v[216:219], v130 offset:36864
	ds_read_b128 v[220:223], v130 offset:38912
	s_waitcnt vmcnt(8)
	s_waitcnt lgkmcnt(0)
	s_barrier
; __device__ __forceinline__ float bflo(unsigned u) { return __uint_as_float(u << 16); }
; __device__ __forceinline__ float bfhi(unsigned u) { return __uint_as_float(u & 0xffff0000u); }
; __device__ __forceinline__ float sigmoidf_(float x) { return frcp_(1.f + __expf(-x)); }
; __device__ __forceinline__ void mma_ktile(const bf16_t* cA, const bf16_t* cB, int fo0, int fo1, f32x4 (&acc)[4][4]) {
; #pragma unroll
;   for (int ks = 0; ks < 2; ++ks) {
;     const int fo = ks ? fo1 : fo0;
;     bf16x8 af[4], bfr[4];
; #pragma unroll
;     for (int i = 0; i < 4; ++i) af[i] = *(const bf16x8*)(cA + i * 16 * LDS_STRIDE + fo);
; #pragma unroll
;     for (int j = 0; j < 4; ++j) bfr[j] = *(const bf16x8*)(cB + j * 16 * LDS_STRIDE + fo);
; #pragma unroll
;     for (int i = 0; i < 4; ++i)
; #pragma unroll
;       for (int j = 0; j < 4; ++j)
;         acc[i][j] = __builtin_amdgcn_mfma_f32_16x16x32_bf16(bfr[j], af[i], acc[i][j], 0, 0, 0);
;   }
; }
; __device__ __forceinline__ void phase_gemm_merge(const Params& p, char* smem) {
;     ...
; #pragma unroll
;       for (int i = 0; i < 4; ++i) {
;         const int m = mt * 128 + wm * 64 + i * 16 + (lane & 15);
; #pragma unroll
;         for (int j = 0; j < 4; ++j) {
;           const int n = nt * 128 + wn * 64 + j * 16 + (lane >> 4) * 4;
;           const uint2 gz = *(const uint2*)(POST + (size_t)m * POST_W + QC_GATE + b * 1024 + n);
;           outv[i][j][0] += sigmoidf_(bflo(gz.x)) * acc[i][j][0];
;           outv[i][j][1] += sigmoidf_(bfhi(gz.x)) * acc[i][j][1];
;           outv[i][j][2] += sigmoidf_(bflo(gz.y)) * acc[i][j][2];
;           outv[i][j][3] += sigmoidf_(bfhi(gz.y)) * acc[i][j][3];
;         }
;       }
	ds_read_b128 v[4:7], v127 offset:16384
	ds_read_b128 v[8:11], v127 offset:18432
	ds_read_b128 v[12:15], v127 offset:20480
	ds_read_b128 v[16:19], v127 offset:22528
	ds_read_b128 v[20:23], v128 offset:49152
	ds_read_b128 v[24:27], v128 offset:51200
	ds_read_b128 v[28:31], v128 offset:53248
	ds_read_b128 v[32:35], v128 offset:55296
	v_mfma_f32_16x16x32_bf16 v[164:167], v[208:211], v[144:147], v[164:167]
	v_mfma_f32_16x16x32_bf16 v[168:171], v[212:215], v[144:147], v[168:171]
	v_mfma_f32_16x16x32_bf16 v[172:175], v[216:219], v[144:147], v[172:175]
	v_mfma_f32_16x16x32_bf16 v[36:39], v[220:223], v[144:147], v[36:39]
	v_mfma_f32_16x16x32_bf16 v[132:135], v[208:211], v[156:159], v[132:135]
	v_mfma_f32_16x16x32_bf16 v[144:147], v[212:215], v[156:159], v[160:163]
	v_mfma_f32_16x16x32_bf16 v[160:163], v[216:219], v[156:159], v[188:191]
	v_mfma_f32_16x16x32_bf16 v[136:139], v[208:211], v[200:203], v[136:139]
	v_mfma_f32_16x16x32_bf16 v[188:191], v[216:219], v[200:203], v[196:199]
	v_mfma_f32_16x16x32_bf16 v[140:143], v[208:211], v[204:207], v[140:143]
	v_mfma_f32_16x16x32_bf16 v[148:151], v[212:215], v[204:207], v[148:151]
	v_mfma_f32_16x16x32_bf16 v[152:155], v[216:219], v[204:207], v[152:155]
	v_mfma_f32_16x16x32_bf16 v[48:51], v[220:223], v[204:207], v[48:51]
	v_mfma_f32_16x16x32_bf16 v[40:43], v[220:223], v[156:159], v[40:43]
	v_mfma_f32_16x16x32_bf16 v[156:159], v[212:215], v[200:203], v[192:195]
	v_mfma_f32_16x16x32_bf16 v[44:47], v[220:223], v[200:203], v[44:47]
	s_waitcnt lgkmcnt(3)
	v_mfma_f32_16x16x32_bf16 v[164:167], v[20:23], v[4:7], v[164:167]
	s_waitcnt lgkmcnt(2)
	v_mfma_f32_16x16x32_bf16 v[168:171], v[24:27], v[4:7], v[168:171]
	s_waitcnt lgkmcnt(1)
	v_mfma_f32_16x16x32_bf16 v[172:175], v[28:31], v[4:7], v[172:175]
	s_waitcnt lgkmcnt(0)
	v_mfma_f32_16x16x32_bf16 v[4:7], v[32:35], v[4:7], v[36:39]
	v_mfma_f32_16x16x32_bf16 v[36:39], v[20:23], v[8:11], v[132:135]
	v_mfma_f32_16x16x32_bf16 v[132:135], v[24:27], v[8:11], v[144:147]
	v_mfma_f32_16x16x32_bf16 v[144:147], v[28:31], v[8:11], v[160:163]
	v_mfma_f32_16x16x32_bf16 v[136:139], v[20:23], v[12:15], v[136:139]
	v_mfma_f32_16x16x32_bf16 v[160:163], v[28:31], v[12:15], v[188:191]
	v_mfma_f32_16x16x32_bf16 v[140:143], v[20:23], v[16:19], v[140:143]
	v_mfma_f32_16x16x32_bf16 v[148:151], v[24:27], v[16:19], v[148:151]
	v_mfma_f32_16x16x32_bf16 v[152:155], v[28:31], v[16:19], v[152:155]
	v_mfma_f32_16x16x32_bf16 v[188:191], v[32:35], v[16:19], v[48:51]
	ds_read_b128 v[16:19], v129 offset:16384
	ds_read_b128 v[20:23], v129 offset:18432
	ds_read_b128 v[192:195], v129 offset:20480
	ds_read_b128 v[126:129], v129 offset:22528
	ds_read_b128 v[196:199], v130 offset:49152
	ds_read_b128 v[200:203], v130 offset:51200
	ds_read_b128 v[204:207], v130 offset:53248
	ds_read_b128 v[208:211], v130 offset:55296
	s_waitcnt lgkmcnt(0)
	s_barrier
	v_mfma_f32_16x16x32_bf16 v[8:11], v[32:35], v[8:11], v[40:43]
	v_mfma_f32_16x16x32_bf16 v[156:159], v[24:27], v[12:15], v[156:159]
	v_mfma_f32_16x16x32_bf16 v[12:15], v[32:35], v[12:15], v[44:47]
	v_mfma_f32_16x16x32_bf16 v[164:167], v[196:199], v[16:19], v[164:167]
	v_mfma_f32_16x16x32_bf16 v[168:171], v[200:203], v[16:19], v[168:171]
	v_mfma_f32_16x16x32_bf16 v[172:175], v[204:207], v[16:19], v[172:175]
	v_mfma_f32_16x16x32_bf16 v[212:215], v[208:211], v[16:19], v[4:7]
	v_mfma_f32_16x16x32_bf16 v[48:51], v[196:199], v[20:23], v[36:39]
	v_mfma_f32_16x16x32_bf16 v[44:47], v[200:203], v[20:23], v[132:135]
	v_mfma_f32_16x16x32_bf16 v[40:43], v[204:207], v[20:23], v[144:147]
	s_nop 1
	v_mov_b32_e32 v133, v166
	v_mov_b32_e32 v166, v165
	v_mov_b32_e32 v132, v164
	v_mfma_f32_16x16x32_bf16 v[36:39], v[208:211], v[20:23], v[8:11]
	v_mfma_f32_16x16x32_bf16 v[20:23], v[208:211], v[192:195], v[12:15]
	v_mfma_f32_16x16x32_bf16 v[16:19], v[196:199], v[126:129], v[140:143]
	v_mfma_f32_16x16x32_bf16 v[12:15], v[200:203], v[126:129], v[148:151]
	v_mfma_f32_16x16x32_bf16 v[8:11], v[204:207], v[126:129], v[152:155]
	v_mfma_f32_16x16x32_bf16 v[4:7], v[208:211], v[126:129], v[188:191]
	v_lshl_add_u64 v[126:127], s[10:11], 0, v[110:111]
	v_add_co_u32_e32 v126, vcc, s59, v126
	v_mfma_f32_16x16x32_bf16 v[32:35], v[196:199], v[192:195], v[136:139]
	s_nop 0
	v_addc_co_u32_e32 v127, vcc, 0, v127, vcc
	s_waitcnt vmcnt(7)
	v_mov_b32_e32 v128, v224
	v_mov_b32_e32 v129, v225
	global_load_dwordx2 v[224:225], v104, s[30:31] offset:3072
	v_mfma_f32_16x16x32_bf16 v[28:31], v[200:203], v[192:195], v[156:159]
	v_lshl_add_u64 v[110:111], v[110:111], 0, s[38:39]
	s_nop 0
	v_lshlrev_b32_e32 v130, 16, v128
	v_and_b32_e32 v128, 0xffff0000, v128
	v_lshlrev_b32_e32 v131, 16, v129
	v_and_b32_e32 v129, 0xffff0000, v129
	v_mul_f32_e32 v128, 0xbfb8aa3b, v128
	v_mul_f32_e32 v129, 0xbfb8aa3b, v129
	v_exp_f32_e32 v128, v128
	v_exp_f32_e32 v129, v129
	v_mul_f32_e32 v130, 0xbfb8aa3b, v130
	v_mul_f32_e32 v131, 0xbfb8aa3b, v131
	v_add_f32_e32 v128, 1.0, v128
	v_add_f32_e32 v129, 1.0, v129
	v_rcp_f32_e32 v128, v128
	v_rcp_f32_e32 v129, v129
	v_exp_f32_e32 v130, v130
	v_exp_f32_e32 v131, v131
	v_mfma_f32_16x16x32_bf16 v[24:27], v[204:207], v[192:195], v[160:163]
	v_fma_f32 v118, v166, v128, v118
	v_fma_f32 v119, v167, v129, v119
	s_waitcnt vmcnt(7)
; __device__ __forceinline__ float bflo(unsigned u) { return __uint_as_float(u << 16); }
; __device__ __forceinline__ float bfhi(unsigned u) { return __uint_as_float(u & 0xffff0000u); }
; __device__ __forceinline__ float sigmoidf_(float x) { return frcp_(1.f + __expf(-x)); }
; #define GLOAD(RA, RB, kt_)                                                         \
;   _Pragma("unroll") for (int i = 0; i < 4; ++i) {                                  \
;     RA[i] = *(const u32x4*)(ap + (size_t)(32 * i) * lda + ((kt_) << 6));           \
;     RB[i] = *(const u32x4*)(bp + (size_t)(32 * i) * ldb + ((kt_) << 6));           \
;   }
; template <bool DEEP>
; __device__ __forceinline__ void gemm_core(const bf16_t* __restrict__ A, int lda, const bf16_t* __restrict__ Bt, int ldb,
;                                           int K, f32x4 (&acc)[4][4], char* smem) {
;     ...
;   u32x4 ra0[4], rb0[4];
;   GLOAD(ra0, rb0, 0);
; __device__ __forceinline__ void phase_gemm_merge(const Params& p, char* smem) {
;     ...
; #pragma unroll
;       for (int i = 0; i < 4; ++i) {
;         const int m = mt * 128 + wm * 64 + i * 16 + (lane & 15);
; #pragma unroll
;         for (int j = 0; j < 4; ++j) {
;           const int n = nt * 128 + wn * 64 + j * 16 + (lane >> 4) * 4;
;           const uint2 gz = *(const uint2*)(POST + (size_t)m * POST_W + QC_GATE + b * 1024 + n);
;           outv[i][j][0] += sigmoidf_(bflo(gz.x)) * acc[i][j][0];
;           outv[i][j][1] += sigmoidf_(bfhi(gz.x)) * acc[i][j][1];
;           outv[i][j][2] += sigmoidf_(bflo(gz.y)) * acc[i][j][2];
;           outv[i][j][3] += sigmoidf_(bfhi(gz.y)) * acc[i][j][3];
;         }
;       }
	v_mov_b32_e32 v128, v226
	v_mov_b32_e32 v129, v227
	global_load_dwordx2 v[226:227], v104, s[30:31] offset:3104
	v_add_f32_e32 v130, 1.0, v130
	v_add_f32_e32 v131, 1.0, v131
	v_rcp_f32_e32 v130, v130
	v_rcp_f32_e32 v131, v131
	s_nop 0
	v_pk_fma_f32 v[120:121], v[132:133], v[130:131], v[120:121]
	v_mov_b32_e32 v133, v170
	v_mov_b32_e32 v170, v169
	v_mov_b32_e32 v132, v168
	s_nop 0
	v_lshlrev_b32_e32 v130, 16, v128
	v_and_b32_e32 v128, 0xffff0000, v128
	v_lshlrev_b32_e32 v131, 16, v129
	v_and_b32_e32 v129, 0xffff0000, v129
	v_mul_f32_e32 v128, 0xbfb8aa3b, v128
	v_mul_f32_e32 v129, 0xbfb8aa3b, v129
	v_exp_f32_e32 v128, v128
	v_exp_f32_e32 v129, v129
	v_mul_f32_e32 v130, 0xbfb8aa3b, v130
	v_mul_f32_e32 v131, 0xbfb8aa3b, v131
	v_add_f32_e32 v128, 1.0, v128
	v_add_f32_e32 v129, 1.0, v129
	v_rcp_f32_e32 v128, v128
	v_rcp_f32_e32 v129, v129
	v_exp_f32_e32 v130, v130
	v_exp_f32_e32 v131, v131
	v_pk_fma_f32 v[114:115], v[170:171], v[128:129], v[114:115]
	v_lshrrev_b32_e32 v202, 3, v178
	v_lshrrev_b32_e32 v203, 4, v178
	v_xor_b32_e32 v203, v203, v178
	v_lshlrev_b32_e32 v203, 4, v203
	v_and_b32_e32 v203, 0x70, v203
	v_mul_lo_u32 v187, v202, s78
	v_lshlrev_b32_e32 v202, 10, v202
	v_or_b32_e32 v187, v187, v203
	v_or_b32_e32 v202, v202, v203
	v_mov_b32_e32 v176, s16
	v_mov_b32_e32 v177, s17
	v_add_u32_e32 v177, s28, v177
	v_add_co_u32_e32 v176, vcc, s13, v176
	s_nop 1
	v_addc_co_u32_e32 v177, vcc, 0, v177, vcc
	v_add_co_u32_e32 v176, vcc, v187, v176
	s_nop 1
	v_addc_co_u32_e32 v177, vcc, 0, v177, vcc
	v_mov_b32_e32 v200, s14
	v_mov_b32_e32 v201, s15
	v_add_u32_e32 v201, s11, v201
	v_add_co_u32_e32 v200, vcc, s10, v200
	s_nop 1
	v_addc_co_u32_e32 v201, vcc, 0, v201, vcc
	v_add_co_u32_e32 v200, vcc, v202, v200
	s_nop 1
	v_addc_co_u32_e32 v201, vcc, 0, v201, vcc
	v_add_co_u32_e32 v200, vcc, 0x237f8000, v200
	s_nop 1
	v_addc_co_u32_e32 v201, vcc, 0, v201, vcc
	s_mov_b32 m0, s29
	s_nop 0
	global_load_lds_dwordx4 v[176:177], off
	s_add_i32 m0, s29, 0x8000
	s_nop 0
	global_load_lds_dwordx4 v[200:201], off
	v_add_co_u32_e32 v176, vcc, 0x18000, v176
	s_nop 1
	v_addc_co_u32_e32 v177, vcc, 0, v177, vcc
	v_add_co_u32_e32 v200, vcc, 0x8000, v200
	s_nop 1
	v_addc_co_u32_e32 v201, vcc, 0, v201, vcc
	s_add_i32 m0, s29, 0x1000
	s_nop 0
	global_load_lds_dwordx4 v[176:177], off
	s_add_i32 m0, s29, 0x9000
	s_nop 0
	global_load_lds_dwordx4 v[200:201], off
	v_add_co_u32_e32 v176, vcc, 0x18000, v176
	s_nop 1
	v_addc_co_u32_e32 v177, vcc, 0, v177, vcc
	v_add_co_u32_e32 v200, vcc, 0x8000, v200
	s_nop 1
	v_addc_co_u32_e32 v201, vcc, 0, v201, vcc
	s_add_i32 m0, s29, 0x2000
	s_nop 0
	global_load_lds_dwordx4 v[176:177], off
	s_add_i32 m0, s29, 0xa000
	s_nop 0
	global_load_lds_dwordx4 v[200:201], off
	v_add_co_u32_e32 v176, vcc, 0x18000, v176
	s_nop 1
	v_addc_co_u32_e32 v177, vcc, 0, v177, vcc
	v_add_co_u32_e32 v200, vcc, 0x8000, v200
	s_nop 1
	v_addc_co_u32_e32 v201, vcc, 0, v201, vcc
	s_add_i32 m0, s29, 0x3000
	s_nop 0
	global_load_lds_dwordx4 v[176:177], off
	s_add_i32 m0, s29, 0xb000
	s_nop 0
	global_load_lds_dwordx4 v[200:201], off
	s_waitcnt vmcnt(15)
	v_mov_b32_e32 v128, v228
	v_mov_b32_e32 v129, v229
	global_load_dwordx2 v[228:229], v104, s[30:31] offset:3136
	v_add_f32_e32 v130, 1.0, v130
	s_waitcnt vmcnt(15)
	v_mov_b32_e32 v126, v230
	v_mov_b32_e32 v127, v231
	global_load_dwordx2 v[230:231], v104, s[30:31] offset:3168
	v_add_f32_e32 v131, 1.0, v131
	v_rcp_f32_e32 v130, v130
	v_rcp_f32_e32 v131, v131
	s_nop 0
	v_pk_fma_f32 v[116:117], v[132:133], v[130:131], v[116:117]
	v_mov_b32_e32 v133, v174
	v_mov_b32_e32 v174, v173
	v_mov_b32_e32 v132, v172
	s_nop 0
	v_lshlrev_b32_e32 v130, 16, v128
	v_and_b32_e32 v128, 0xffff0000, v128
	v_lshlrev_b32_e32 v131, 16, v129
	v_and_b32_e32 v129, 0xffff0000, v129
	v_mul_f32_e32 v128, 0xbfb8aa3b, v128
	v_mul_f32_e32 v129, 0xbfb8aa3b, v129
	v_exp_f32_e32 v128, v128
	v_exp_f32_e32 v129, v129
	v_mul_f32_e32 v130, 0xbfb8aa3b, v130
	v_mul_f32_e32 v131, 0xbfb8aa3b, v131
	v_add_f32_e32 v128, 1.0, v128
	v_add_f32_e32 v129, 1.0, v129
	v_rcp_f32_e32 v128, v128
	v_rcp_f32_e32 v129, v129
	v_exp_f32_e32 v130, v130
	v_exp_f32_e32 v131, v131
	v_pk_fma_f32 v[108:109], v[174:175], v[128:129], v[108:109]
	s_nop 0
	v_lshlrev_b32_e32 v128, 16, v126
	v_and_b32_e32 v126, 0xffff0000, v126
	v_lshlrev_b32_e32 v129, 16, v127
	v_and_b32_e32 v127, 0xffff0000, v127
	v_mul_f32_e32 v126, 0xbfb8aa3b, v126
	v_mul_f32_e32 v127, 0xbfb8aa3b, v127
	v_exp_f32_e32 v126, v126
	v_exp_f32_e32 v127, v127
	v_mul_f32_e32 v128, 0xbfb8aa3b, v128
	v_mul_f32_e32 v129, 0xbfb8aa3b, v129
	v_add_f32_e32 v130, 1.0, v130
	v_add_f32_e32 v131, 1.0, v131
	v_exp_f32_e32 v128, v128
	v_exp_f32_e32 v129, v129
	v_rcp_f32_e32 v130, v130
	v_rcp_f32_e32 v131, v131
	v_add_f32_e32 v126, 1.0, v126
	v_add_f32_e32 v127, 1.0, v127
	v_rcp_f32_e32 v126, v126
	v_rcp_f32_e32 v127, v127
	v_add_f32_e32 v128, 1.0, v128
	v_add_f32_e32 v129, 1.0, v129
	v_pk_fma_f32 v[112:113], v[132:133], v[130:131], v[112:113]
	v_rcp_f32_e32 v128, v128
	v_rcp_f32_e32 v129, v129
	v_mov_b32_e32 v131, v214
	v_mov_b32_e32 v214, v213
	v_pk_fma_f32 v[98:99], v[214:215], v[126:127], v[98:99]
	v_lshl_add_u64 v[126:127], s[10:11], 0, v[106:107]
	v_add_co_u32_e32 v126, vcc, s59, v126
	v_mov_b32_e32 v130, v212
	s_nop 0
	v_addc_co_u32_e32 v127, vcc, 0, v127, vcc
	v_pk_fma_f32 v[100:101], v[130:131], v[128:129], v[100:101]
	s_waitcnt vmcnt(15)
	v_mov_b32_e32 v128, v232
	v_mov_b32_e32 v129, v233
	global_load_dwordx2 v[232:233], v102, s[30:31] offset:3072
	v_mov_b32_e32 v132, v48
	v_mov_b32_e32 v133, v50
	v_mov_b32_e32 v50, v49
	s_waitcnt vmcnt(15)
; __device__ __forceinline__ float bflo(unsigned u) { return __uint_as_float(u << 16); }
; __device__ __forceinline__ float bfhi(unsigned u) { return __uint_as_float(u & 0xffff0000u); }
; __device__ __forceinline__ float sigmoidf_(float x) { return frcp_(1.f + __expf(-x)); }
; __device__ __forceinline__ void phase_gemm_merge(const Params& p, char* smem) {
;     ...
; #pragma unroll
;       for (int i = 0; i < 4; ++i) {
;         const int m = mt * 128 + wm * 64 + i * 16 + (lane & 15);
; #pragma unroll
;         for (int j = 0; j < 4; ++j) {
;           const int n = nt * 128 + wn * 64 + j * 16 + (lane >> 4) * 4;
;           const uint2 gz = *(const uint2*)(POST + (size_t)m * POST_W + QC_GATE + b * 1024 + n);
;           outv[i][j][0] += sigmoidf_(bflo(gz.x)) * acc[i][j][0];
;           outv[i][j][1] += sigmoidf_(bfhi(gz.x)) * acc[i][j][1];
;           outv[i][j][2] += sigmoidf_(bflo(gz.y)) * acc[i][j][2];
;           outv[i][j][3] += sigmoidf_(bfhi(gz.y)) * acc[i][j][3];
;         }
;       }
	v_mov_b32_e32 v48, v234
	v_mov_b32_e32 v49, v235
	global_load_dwordx2 v[234:235], v102, s[30:31] offset:3104
	v_lshl_add_u64 v[106:107], v[106:107], 0, s[38:39]
	s_nop 0
	v_lshlrev_b32_e32 v130, 16, v128
	v_and_b32_e32 v128, 0xffff0000, v128
	v_lshlrev_b32_e32 v131, 16, v129
	v_and_b32_e32 v129, 0xffff0000, v129
	v_mul_f32_e32 v128, 0xbfb8aa3b, v128
	v_mul_f32_e32 v129, 0xbfb8aa3b, v129
	v_exp_f32_e32 v128, v128
	v_exp_f32_e32 v129, v129
	v_mul_f32_e32 v130, 0xbfb8aa3b, v130
	v_mul_f32_e32 v131, 0xbfb8aa3b, v131
	v_add_f32_e32 v128, 1.0, v128
	v_add_f32_e32 v129, 1.0, v129
	v_rcp_f32_e32 v128, v128
	v_rcp_f32_e32 v129, v129
	v_exp_f32_e32 v130, v130
	v_exp_f32_e32 v131, v131
	v_pk_fma_f32 v[94:95], v[50:51], v[128:129], v[94:95]
	s_nop 0
	v_lshlrev_b32_e32 v50, 16, v48
	v_and_b32_e32 v48, 0xffff0000, v48
	v_lshlrev_b32_e32 v51, 16, v49
	v_and_b32_e32 v49, 0xffff0000, v49
	v_mov_b32_e32 v128, v44
	v_mov_b32_e32 v129, v46
	v_mov_b32_e32 v46, v45
	s_waitcnt vmcnt(15)
	v_mov_b32_e32 v44, v236
	v_mov_b32_e32 v45, v237
	global_load_dwordx2 v[236:237], v102, s[30:31] offset:3136
	v_mul_f32_e32 v48, 0xbfb8aa3b, v48
	v_mul_f32_e32 v49, 0xbfb8aa3b, v49
	v_exp_f32_e32 v48, v48
	v_exp_f32_e32 v49, v49
	v_mul_f32_e32 v50, 0xbfb8aa3b, v50
	v_mul_f32_e32 v51, 0xbfb8aa3b, v51
	v_add_f32_e32 v48, 1.0, v48
	v_add_f32_e32 v49, 1.0, v49
	v_rcp_f32_e32 v48, v48
	v_rcp_f32_e32 v49, v49
	v_exp_f32_e32 v50, v50
	v_exp_f32_e32 v51, v51
	v_add_f32_e32 v130, 1.0, v130
	v_pk_fma_f32 v[90:91], v[46:47], v[48:49], v[90:91]
	v_mov_b32_e32 v48, v40
	v_mov_b32_e32 v49, v42
	v_mov_b32_e32 v42, v41
	s_waitcnt vmcnt(15)
	v_mov_b32_e32 v40, v238
	v_mov_b32_e32 v41, v239
	global_load_dwordx2 v[238:239], v102, s[30:31] offset:3168
	v_add_f32_e32 v131, 1.0, v131
	v_add_f32_e32 v50, 1.0, v50
	v_add_f32_e32 v51, 1.0, v51
	v_rcp_f32_e32 v130, v130
	v_rcp_f32_e32 v131, v131
	v_rcp_f32_e32 v50, v50
	v_rcp_f32_e32 v51, v51
	v_pk_fma_f32 v[96:97], v[132:133], v[130:131], v[96:97]
	v_pk_fma_f32 v[92:93], v[128:129], v[50:51], v[92:93]
	s_nop 0
	v_lshlrev_b32_e32 v46, 16, v44
	v_and_b32_e32 v44, 0xffff0000, v44
	v_lshlrev_b32_e32 v47, 16, v45
	v_and_b32_e32 v45, 0xffff0000, v45
	v_mul_f32_e32 v44, 0xbfb8aa3b, v44
	v_mul_f32_e32 v45, 0xbfb8aa3b, v45
	v_exp_f32_e32 v44, v44
	v_exp_f32_e32 v45, v45
	v_mul_f32_e32 v46, 0xbfb8aa3b, v46
	v_mul_f32_e32 v47, 0xbfb8aa3b, v47
	v_add_f32_e32 v44, 1.0, v44
	v_add_f32_e32 v45, 1.0, v45
	v_rcp_f32_e32 v44, v44
	v_rcp_f32_e32 v45, v45
	v_exp_f32_e32 v46, v46
	v_exp_f32_e32 v47, v47
	v_pk_fma_f32 v[86:87], v[42:43], v[44:45], v[86:87]
	s_nop 0
	v_lshlrev_b32_e32 v42, 16, v40
	v_and_b32_e32 v40, 0xffff0000, v40
	v_lshlrev_b32_e32 v43, 16, v41
	v_and_b32_e32 v41, 0xffff0000, v41
	v_mul_f32_e32 v40, 0xbfb8aa3b, v40
	v_mul_f32_e32 v41, 0xbfb8aa3b, v41
	v_exp_f32_e32 v40, v40
	v_exp_f32_e32 v41, v41
	v_mov_b32_e32 v44, v36
	v_mov_b32_e32 v45, v38
	v_add_f32_e32 v40, 1.0, v40
	v_add_f32_e32 v41, 1.0, v41
	v_rcp_f32_e32 v40, v40
	v_rcp_f32_e32 v41, v41
	v_mov_b32_e32 v38, v37
	v_lshl_add_u64 v[36:37], s[10:11], 0, v[104:105]
	v_add_co_u32_e32 v36, vcc, s59, v36
	v_pk_fma_f32 v[82:83], v[38:39], v[40:41], v[82:83]
	s_nop 0
	v_addc_co_u32_e32 v37, vcc, 0, v37, vcc
	s_waitcnt vmcnt(15)
	v_mov_b32_e32 v38, v224
	v_mov_b32_e32 v39, v225
	v_mul_f32_e32 v42, 0xbfb8aa3b, v42
	v_mul_f32_e32 v43, 0xbfb8aa3b, v43
	v_exp_f32_e32 v42, v42
	v_exp_f32_e32 v43, v43
	v_add_f32_e32 v46, 1.0, v46
	v_add_f32_e32 v47, 1.0, v47
	v_add_f32_e32 v42, 1.0, v42
	v_add_f32_e32 v43, 1.0, v43
	v_rcp_f32_e32 v42, v42
	v_rcp_f32_e32 v43, v43
	v_rcp_f32_e32 v46, v46
	v_rcp_f32_e32 v47, v47
	v_lshl_add_u64 v[104:105], v[104:105], 0, s[38:39]
	v_pk_fma_f32 v[84:85], v[44:45], v[42:43], v[84:85]
	v_mov_b32_e32 v42, v32
	v_mov_b32_e32 v43, v34
	v_mov_b32_e32 v34, v33
	s_waitcnt vmcnt(14)
	v_mov_b32_e32 v32, v226
	v_mov_b32_e32 v33, v227
	v_pk_fma_f32 v[88:89], v[48:49], v[46:47], v[88:89]
	s_nop 0
	v_lshlrev_b32_e32 v40, 16, v38
	v_and_b32_e32 v38, 0xffff0000, v38
	v_lshlrev_b32_e32 v41, 16, v39
	v_and_b32_e32 v39, 0xffff0000, v39
	v_mul_f32_e32 v38, 0xbfb8aa3b, v38
	v_mul_f32_e32 v39, 0xbfb8aa3b, v39
	v_exp_f32_e32 v38, v38
	v_exp_f32_e32 v39, v39
	v_mul_f32_e32 v40, 0xbfb8aa3b, v40
	v_mul_f32_e32 v41, 0xbfb8aa3b, v41
	v_add_f32_e32 v38, 1.0, v38
	v_add_f32_e32 v39, 1.0, v39
	v_rcp_f32_e32 v38, v38
	v_rcp_f32_e32 v39, v39
	v_exp_f32_e32 v40, v40
	v_exp_f32_e32 v41, v41
	v_pk_fma_f32 v[78:79], v[34:35], v[38:39], v[78:79]
	s_nop 0
	v_lshlrev_b32_e32 v34, 16, v32
	v_and_b32_e32 v32, 0xffff0000, v32
	v_lshlrev_b32_e32 v35, 16, v33
	v_and_b32_e32 v33, 0xffff0000, v33
	v_mov_b32_e32 v38, v28
	v_mov_b32_e32 v39, v30
	v_mov_b32_e32 v30, v29
	s_waitcnt vmcnt(5)
	v_mov_b32_e32 v28, v228
	v_mov_b32_e32 v29, v229
	v_mul_f32_e32 v32, 0xbfb8aa3b, v32
	v_mul_f32_e32 v33, 0xbfb8aa3b, v33
	v_exp_f32_e32 v32, v32
	v_exp_f32_e32 v33, v33
	v_mul_f32_e32 v34, 0xbfb8aa3b, v34
	v_mul_f32_e32 v35, 0xbfb8aa3b, v35
	v_add_f32_e32 v32, 1.0, v32
	v_add_f32_e32 v33, 1.0, v33
	v_rcp_f32_e32 v32, v32
	v_rcp_f32_e32 v33, v33
	v_exp_f32_e32 v34, v34
	v_exp_f32_e32 v35, v35
	v_add_f32_e32 v40, 1.0, v40
	v_pk_fma_f32 v[74:75], v[30:31], v[32:33], v[74:75]
	v_mov_b32_e32 v32, v24
	v_mov_b32_e32 v33, v26
	v_mov_b32_e32 v26, v25
	s_waitcnt vmcnt(4)
; __device__ __forceinline__ float bflo(unsigned u) { return __uint_as_float(u << 16); }
; __device__ __forceinline__ float bfhi(unsigned u) { return __uint_as_float(u & 0xffff0000u); }
; __device__ __forceinline__ float sigmoidf_(float x) { return frcp_(1.f + __expf(-x)); }
; __device__ __forceinline__ void phase_gemm_merge(const Params& p, char* smem) {
;     ...
;     for (int b = 0; b < 3; ++b) {
;       f32x4 acc[4][4];
; #pragma unroll
;       for (int i = 0; i < 4; ++i)
; #pragma unroll
;         for (int j = 0; j < 4; ++j) acc[i][j] = (f32x4){0.f, 0.f, 0.f, 0.f};
;       gemm_core<false>(BR + (size_t)mt * 128 * 1536 + b * 512, 1536, W + ((size_t)b * 1024 + nt * 128) * 512, 512, 512, acc, smem);
; #pragma unroll
;       for (int i = 0; i < 4; ++i) {
;         const int m = mt * 128 + wm * 64 + i * 16 + (lane & 15);
; #pragma unroll
;         for (int j = 0; j < 4; ++j) {
;           const int n = nt * 128 + wn * 64 + j * 16 + (lane >> 4) * 4;
;           const uint2 gz = *(const uint2*)(POST + (size_t)m * POST_W + QC_GATE + b * 1024 + n);
;           outv[i][j][0] += sigmoidf_(bflo(gz.x)) * acc[i][j][0];
;           outv[i][j][1] += sigmoidf_(bfhi(gz.x)) * acc[i][j][1];
;           outv[i][j][2] += sigmoidf_(bflo(gz.y)) * acc[i][j][2];
;           outv[i][j][3] += sigmoidf_(bfhi(gz.y)) * acc[i][j][3];
;         }
;       }
	v_mov_b32_e32 v24, v230
	v_mov_b32_e32 v25, v231
	v_add_f32_e32 v41, 1.0, v41
	v_add_f32_e32 v34, 1.0, v34
	v_add_f32_e32 v35, 1.0, v35
	v_rcp_f32_e32 v40, v40
	v_rcp_f32_e32 v41, v41
	v_rcp_f32_e32 v34, v34
	v_rcp_f32_e32 v35, v35
	v_pk_fma_f32 v[80:81], v[42:43], v[40:41], v[80:81]
	v_pk_fma_f32 v[76:77], v[38:39], v[34:35], v[76:77]
	s_nop 0
	v_lshlrev_b32_e32 v30, 16, v28
	v_and_b32_e32 v28, 0xffff0000, v28
	v_lshlrev_b32_e32 v31, 16, v29
	v_and_b32_e32 v29, 0xffff0000, v29
	v_mul_f32_e32 v28, 0xbfb8aa3b, v28
	v_mul_f32_e32 v29, 0xbfb8aa3b, v29
	v_exp_f32_e32 v28, v28
	v_exp_f32_e32 v29, v29
	v_mul_f32_e32 v30, 0xbfb8aa3b, v30
	v_mul_f32_e32 v31, 0xbfb8aa3b, v31
	v_add_f32_e32 v28, 1.0, v28
	v_add_f32_e32 v29, 1.0, v29
	v_rcp_f32_e32 v28, v28
	v_rcp_f32_e32 v29, v29
	v_exp_f32_e32 v30, v30
	v_exp_f32_e32 v31, v31
	v_pk_fma_f32 v[70:71], v[26:27], v[28:29], v[70:71]
	s_nop 0
	v_lshlrev_b32_e32 v26, 16, v24
	v_and_b32_e32 v24, 0xffff0000, v24
	v_lshlrev_b32_e32 v27, 16, v25
	v_and_b32_e32 v25, 0xffff0000, v25
	v_mul_f32_e32 v24, 0xbfb8aa3b, v24
	v_mul_f32_e32 v25, 0xbfb8aa3b, v25
	v_exp_f32_e32 v24, v24
	v_exp_f32_e32 v25, v25
	v_mov_b32_e32 v28, v20
	v_mov_b32_e32 v29, v22
	v_add_f32_e32 v24, 1.0, v24
	v_add_f32_e32 v25, 1.0, v25
	v_rcp_f32_e32 v24, v24
	v_rcp_f32_e32 v25, v25
	v_mov_b32_e32 v22, v21
	v_lshl_add_u64 v[20:21], s[10:11], 0, v[102:103]
	v_add_co_u32_e32 v20, vcc, s59, v20
	v_pk_fma_f32 v[66:67], v[22:23], v[24:25], v[66:67]
	s_nop 0
	v_addc_co_u32_e32 v21, vcc, 0, v21, vcc
	s_waitcnt vmcnt(3)
	v_mov_b32_e32 v22, v232
	v_mov_b32_e32 v23, v233
	v_mul_f32_e32 v26, 0xbfb8aa3b, v26
	v_mul_f32_e32 v27, 0xbfb8aa3b, v27
	v_exp_f32_e32 v26, v26
	v_exp_f32_e32 v27, v27
	v_add_f32_e32 v30, 1.0, v30
	v_add_f32_e32 v31, 1.0, v31
	v_add_f32_e32 v26, 1.0, v26
	v_add_f32_e32 v27, 1.0, v27
	v_rcp_f32_e32 v26, v26
	v_rcp_f32_e32 v27, v27
	v_rcp_f32_e32 v30, v30
	v_rcp_f32_e32 v31, v31
	v_lshl_add_u64 v[102:103], v[102:103], 0, s[38:39]
	v_pk_fma_f32 v[68:69], v[28:29], v[26:27], v[68:69]
	v_mov_b32_e32 v26, v16
	v_mov_b32_e32 v27, v18
	v_mov_b32_e32 v18, v17
	s_waitcnt vmcnt(2)
	v_mov_b32_e32 v16, v234
	v_mov_b32_e32 v17, v235
	v_pk_fma_f32 v[72:73], v[32:33], v[30:31], v[72:73]
	s_nop 0
	v_lshlrev_b32_e32 v24, 16, v22
	v_and_b32_e32 v22, 0xffff0000, v22
	v_lshlrev_b32_e32 v25, 16, v23
	v_and_b32_e32 v23, 0xffff0000, v23
	v_mul_f32_e32 v22, 0xbfb8aa3b, v22
	v_mul_f32_e32 v23, 0xbfb8aa3b, v23
	v_exp_f32_e32 v22, v22
	v_exp_f32_e32 v23, v23
	v_mul_f32_e32 v24, 0xbfb8aa3b, v24
	v_mul_f32_e32 v25, 0xbfb8aa3b, v25
	v_add_f32_e32 v22, 1.0, v22
	v_add_f32_e32 v23, 1.0, v23
	v_rcp_f32_e32 v22, v22
	v_rcp_f32_e32 v23, v23
	v_exp_f32_e32 v24, v24
	v_exp_f32_e32 v25, v25
	v_pk_fma_f32 v[62:63], v[18:19], v[22:23], v[62:63]
	s_nop 0
	v_lshlrev_b32_e32 v18, 16, v16
	v_and_b32_e32 v16, 0xffff0000, v16
	v_lshlrev_b32_e32 v19, 16, v17
	v_and_b32_e32 v17, 0xffff0000, v17
	v_mov_b32_e32 v22, v12
	v_mov_b32_e32 v23, v14
	v_mov_b32_e32 v14, v13
	s_waitcnt vmcnt(1)
	v_mov_b32_e32 v12, v236
	v_mov_b32_e32 v13, v237
	v_mul_f32_e32 v16, 0xbfb8aa3b, v16
	v_mul_f32_e32 v17, 0xbfb8aa3b, v17
	v_exp_f32_e32 v16, v16
	v_exp_f32_e32 v17, v17
	v_mul_f32_e32 v18, 0xbfb8aa3b, v18
	v_mul_f32_e32 v19, 0xbfb8aa3b, v19
	v_add_f32_e32 v16, 1.0, v16
	v_add_f32_e32 v17, 1.0, v17
	v_rcp_f32_e32 v16, v16
	v_rcp_f32_e32 v17, v17
	v_exp_f32_e32 v18, v18
	v_exp_f32_e32 v19, v19
	v_add_f32_e32 v24, 1.0, v24
	v_pk_fma_f32 v[58:59], v[14:15], v[16:17], v[58:59]
	v_mov_b32_e32 v16, v8
	v_mov_b32_e32 v17, v10
	v_mov_b32_e32 v10, v9
	s_waitcnt vmcnt(0)
	v_mov_b32_e32 v8, v238
	v_mov_b32_e32 v9, v239
	v_add_f32_e32 v25, 1.0, v25
	v_add_f32_e32 v18, 1.0, v18
	v_add_f32_e32 v19, 1.0, v19
	v_rcp_f32_e32 v24, v24
	v_rcp_f32_e32 v25, v25
	v_rcp_f32_e32 v18, v18
	v_rcp_f32_e32 v19, v19
	v_pk_fma_f32 v[64:65], v[26:27], v[24:25], v[64:65]
	v_pk_fma_f32 v[60:61], v[22:23], v[18:19], v[60:61]
	s_nop 0
	v_lshlrev_b32_e32 v14, 16, v12
	v_and_b32_e32 v12, 0xffff0000, v12
	v_lshlrev_b32_e32 v15, 16, v13
	v_and_b32_e32 v13, 0xffff0000, v13
	v_mul_f32_e32 v12, 0xbfb8aa3b, v12
	v_mul_f32_e32 v13, 0xbfb8aa3b, v13
	v_exp_f32_e32 v12, v12
	v_exp_f32_e32 v13, v13
	v_mul_f32_e32 v14, 0xbfb8aa3b, v14
	v_mul_f32_e32 v15, 0xbfb8aa3b, v15
	v_add_f32_e32 v12, 1.0, v12
	v_add_f32_e32 v13, 1.0, v13
	v_rcp_f32_e32 v12, v12
	v_rcp_f32_e32 v13, v13
	v_exp_f32_e32 v14, v14
	v_exp_f32_e32 v15, v15
	v_pk_fma_f32 v[54:55], v[10:11], v[12:13], v[54:55]
	s_nop 0
	v_lshlrev_b32_e32 v10, 16, v8
	v_and_b32_e32 v8, 0xffff0000, v8
	v_lshlrev_b32_e32 v11, 16, v9
	v_and_b32_e32 v9, 0xffff0000, v9
	v_mul_f32_e32 v10, 0xbfb8aa3b, v10
	v_mul_f32_e32 v8, 0xbfb8aa3b, v8
	v_mul_f32_e32 v11, 0xbfb8aa3b, v11
	v_mul_f32_e32 v9, 0xbfb8aa3b, v9
	v_exp_f32_e32 v10, v10
	v_exp_f32_e32 v8, v8
	v_exp_f32_e32 v11, v11
	v_exp_f32_e32 v9, v9
	v_add_f32_e32 v14, 1.0, v14
	v_add_f32_e32 v15, 1.0, v15
	v_add_f32_e32 v10, 1.0, v10
	v_add_f32_e32 v8, 1.0, v8
	v_add_f32_e32 v11, 1.0, v11
	v_add_f32_e32 v9, 1.0, v9
	v_rcp_f32_e32 v14, v14
	v_rcp_f32_e32 v15, v15
	v_rcp_f32_e32 v10, v10
	v_rcp_f32_e32 v8, v8
	v_rcp_f32_e32 v11, v11
	v_rcp_f32_e32 v9, v9
	v_mov_b32_e32 v12, v4
	v_mov_b32_e32 v13, v6
	v_mov_b32_e32 v6, v5
	v_pk_fma_f32 v[56:57], v[16:17], v[14:15], v[56:57]
	v_pk_fma_f32 v[0:1], v[12:13], v[10:11], v[0:1]
	v_pk_fma_f32 v[52:53], v[6:7], v[8:9], v[52:53]
	s_cmpk_eq_i32 s16, 0xc00
	s_cbranch_scc0 .LBB0_21
; __device__ __forceinline__ unsigned pack2(float a, float b) { return (unsigned)f2bf(a) | ((unsigned)f2bf(b) << 16); }
; __device__ __forceinline__ void phase_gemm_merge(const Params& p, char* smem) {
;     ...
; #pragma unroll
;     for (int i = 0; i < 4; ++i) {
;       const int m = mt * 128 + wm * 64 + i * 16 + (lane & 15);
; #pragma unroll
;       for (int j = 0; j < 4; ++j) {
;         const int n = nt * 128 + wn * 64 + j * 16 + (lane >> 4) * 4;
;         uint2 o;
;         o.x = pack2(outv[i][j][0], outv[i][j][1]);
;         o.y = pack2(outv[i][j][2], outv[i][j][3]);
;         *(uint2*)(MG + (size_t)m * 1024 + n) = o;
;       }
;     }
	v_lshl_add_u32 v4, s27, 7, v2
	v_and_b32_sdwa v15, v120, v183 dst_sel:DWORD dst_unused:UNUSED_PAD src0_sel:WORD_1 src1_sel:DWORD
	v_or_b32_e32 v6, s12, v122
	v_ashrrev_i32_e32 v5, 31, v4
	v_readlane_b32 s12, v244, 7
	v_add3_u32 v16, v120, v15, s37
	v_and_b32_sdwa v15, v119, v183 dst_sel:DWORD dst_unused:UNUSED_PAD src0_sel:WORD_1 src1_sel:DWORD
	v_and_b32_sdwa v17, v118, v183 dst_sel:DWORD dst_unused:UNUSED_PAD src0_sel:WORD_1 src1_sel:DWORD
	v_or_b32_e32 v8, 48, v4
	v_ashrrev_i32_e32 v7, 31, v6
	v_or_b32_e32 v10, 16, v4
	v_or_b32_e32 v12, 32, v4
	v_lshlrev_b64 v[4:5], 11, v[4:5]
	v_readlane_b32 s13, v244, 8
	v_and_b32_sdwa v14, v121, v183 dst_sel:DWORD dst_unused:UNUSED_PAD src0_sel:WORD_1 src1_sel:DWORD
	v_add3_u32 v15, v119, v15, s37
	v_add3_u32 v17, v118, v17, s37
	v_lshl_add_u64 v[4:5], s[12:13], 0, v[4:5]
	v_lshlrev_b64 v[6:7], 1, v[6:7]
	v_add3_u32 v14, v121, v14, s37
	v_and_b32_e32 v15, 0xffff0000, v15
	v_and_b32_e32 v17, 0xffff0000, v17
	v_lshl_add_u64 v[4:5], v[4:5], 0, v[6:7]
	v_or_b32_sdwa v15, v15, v14 dst_sel:DWORD dst_unused:UNUSED_PAD src0_sel:DWORD src1_sel:WORD_1
	v_or_b32_sdwa v14, v17, v16 dst_sel:DWORD dst_unused:UNUSED_PAD src0_sel:DWORD src1_sel:WORD_1
	global_store_dwordx2 v[4:5], v[14:15], off
	v_and_b32_sdwa v15, v116, v183 dst_sel:DWORD dst_unused:UNUSED_PAD src0_sel:WORD_1 src1_sel:DWORD
	v_add3_u32 v16, v116, v15, s37
	v_and_b32_sdwa v15, v115, v183 dst_sel:DWORD dst_unused:UNUSED_PAD src0_sel:WORD_1 src1_sel:DWORD
	v_and_b32_sdwa v17, v114, v183 dst_sel:DWORD dst_unused:UNUSED_PAD src0_sel:WORD_1 src1_sel:DWORD
	v_and_b32_sdwa v14, v117, v183 dst_sel:DWORD dst_unused:UNUSED_PAD src0_sel:WORD_1 src1_sel:DWORD
	v_add3_u32 v15, v115, v15, s37
	v_add3_u32 v17, v114, v17, s37
	v_add3_u32 v14, v117, v14, s37
	v_and_b32_e32 v15, 0xffff0000, v15
	v_and_b32_e32 v17, 0xffff0000, v17
	v_or_b32_sdwa v15, v15, v14 dst_sel:DWORD dst_unused:UNUSED_PAD src0_sel:DWORD src1_sel:WORD_1
	v_or_b32_sdwa v14, v17, v16 dst_sel:DWORD dst_unused:UNUSED_PAD src0_sel:DWORD src1_sel:WORD_1
	global_store_dwordx2 v[4:5], v[14:15], off offset:32
	v_and_b32_sdwa v15, v112, v183 dst_sel:DWORD dst_unused:UNUSED_PAD src0_sel:WORD_1 src1_sel:DWORD
	v_add3_u32 v16, v112, v15, s37
	v_and_b32_sdwa v15, v109, v183 dst_sel:DWORD dst_unused:UNUSED_PAD src0_sel:WORD_1 src1_sel:DWORD
	v_and_b32_sdwa v17, v108, v183 dst_sel:DWORD dst_unused:UNUSED_PAD src0_sel:WORD_1 src1_sel:DWORD
	v_and_b32_sdwa v14, v113, v183 dst_sel:DWORD dst_unused:UNUSED_PAD src0_sel:WORD_1 src1_sel:DWORD
	v_add3_u32 v15, v109, v15, s37
	v_add3_u32 v17, v108, v17, s37
	v_add3_u32 v14, v113, v14, s37
	v_and_b32_e32 v15, 0xffff0000, v15
	v_and_b32_e32 v17, 0xffff0000, v17
	v_or_b32_sdwa v15, v15, v14 dst_sel:DWORD dst_unused:UNUSED_PAD src0_sel:DWORD src1_sel:WORD_1
	v_or_b32_sdwa v14, v17, v16 dst_sel:DWORD dst_unused:UNUSED_PAD src0_sel:DWORD src1_sel:WORD_1
	global_store_dwordx2 v[4:5], v[14:15], off offset:64
	v_and_b32_sdwa v15, v100, v183 dst_sel:DWORD dst_unused:UNUSED_PAD src0_sel:WORD_1 src1_sel:DWORD
	v_add3_u32 v16, v100, v15, s37
	v_and_b32_sdwa v15, v99, v183 dst_sel:DWORD dst_unused:UNUSED_PAD src0_sel:WORD_1 src1_sel:DWORD
	v_and_b32_sdwa v17, v98, v183 dst_sel:DWORD dst_unused:UNUSED_PAD src0_sel:WORD_1 src1_sel:DWORD
	v_and_b32_sdwa v14, v101, v183 dst_sel:DWORD dst_unused:UNUSED_PAD src0_sel:WORD_1 src1_sel:DWORD
	v_add3_u32 v15, v99, v15, s37
	v_add3_u32 v17, v98, v17, s37
	v_add3_u32 v14, v101, v14, s37
	v_and_b32_e32 v15, 0xffff0000, v15
	v_and_b32_e32 v17, 0xffff0000, v17
	v_ashrrev_i32_e32 v11, 31, v10
	v_or_b32_sdwa v15, v15, v14 dst_sel:DWORD dst_unused:UNUSED_PAD src0_sel:DWORD src1_sel:WORD_1
	v_or_b32_sdwa v14, v17, v16 dst_sel:DWORD dst_unused:UNUSED_PAD src0_sel:DWORD src1_sel:WORD_1
	global_store_dwordx2 v[4:5], v[14:15], off offset:96
	v_lshlrev_b64 v[4:5], 11, v[10:11]
	v_and_b32_sdwa v11, v96, v183 dst_sel:DWORD dst_unused:UNUSED_PAD src0_sel:WORD_1 src1_sel:DWORD
	v_add3_u32 v14, v96, v11, s37
	v_and_b32_sdwa v11, v95, v183 dst_sel:DWORD dst_unused:UNUSED_PAD src0_sel:WORD_1 src1_sel:DWORD
	v_and_b32_sdwa v15, v94, v183 dst_sel:DWORD dst_unused:UNUSED_PAD src0_sel:WORD_1 src1_sel:DWORD
	v_and_b32_sdwa v10, v97, v183 dst_sel:DWORD dst_unused:UNUSED_PAD src0_sel:WORD_1 src1_sel:DWORD
	v_add3_u32 v11, v95, v11, s37
	v_add3_u32 v15, v94, v15, s37
	v_lshl_add_u64 v[4:5], s[12:13], 0, v[4:5]
	v_add3_u32 v10, v97, v10, s37
	v_and_b32_e32 v11, 0xffff0000, v11
	v_and_b32_e32 v15, 0xffff0000, v15
	v_lshl_add_u64 v[4:5], v[4:5], 0, v[6:7]
	v_or_b32_sdwa v11, v11, v10 dst_sel:DWORD dst_unused:UNUSED_PAD src0_sel:DWORD src1_sel:WORD_1
	v_or_b32_sdwa v10, v15, v14 dst_sel:DWORD dst_unused:UNUSED_PAD src0_sel:DWORD src1_sel:WORD_1
	global_store_dwordx2 v[4:5], v[10:11], off
	v_and_b32_sdwa v11, v92, v183 dst_sel:DWORD dst_unused:UNUSED_PAD src0_sel:WORD_1 src1_sel:DWORD
	v_add3_u32 v14, v92, v11, s37
	v_and_b32_sdwa v11, v91, v183 dst_sel:DWORD dst_unused:UNUSED_PAD src0_sel:WORD_1 src1_sel:DWORD
	v_and_b32_sdwa v15, v90, v183 dst_sel:DWORD dst_unused:UNUSED_PAD src0_sel:WORD_1 src1_sel:DWORD
	v_and_b32_sdwa v10, v93, v183 dst_sel:DWORD dst_unused:UNUSED_PAD src0_sel:WORD_1 src1_sel:DWORD
	v_add3_u32 v11, v91, v11, s37
	v_add3_u32 v15, v90, v15, s37
	v_add3_u32 v10, v93, v10, s37
	v_and_b32_e32 v11, 0xffff0000, v11
	v_and_b32_e32 v15, 0xffff0000, v15
	v_or_b32_sdwa v11, v11, v10 dst_sel:DWORD dst_unused:UNUSED_PAD src0_sel:DWORD src1_sel:WORD_1
	v_or_b32_sdwa v10, v15, v14 dst_sel:DWORD dst_unused:UNUSED_PAD src0_sel:DWORD src1_sel:WORD_1
	global_store_dwordx2 v[4:5], v[10:11], off offset:32
	v_and_b32_sdwa v11, v88, v183 dst_sel:DWORD dst_unused:UNUSED_PAD src0_sel:WORD_1 src1_sel:DWORD
; __device__ __forceinline__ unsigned pack2(float a, float b) { return (unsigned)f2bf(a) | ((unsigned)f2bf(b) << 16); }
; __device__ __forceinline__ void phase_gemm_merge(const Params& p, char* smem) {
;     ...
; #pragma unroll
;     for (int i = 0; i < 4; ++i) {
;       const int m = mt * 128 + wm * 64 + i * 16 + (lane & 15);
; #pragma unroll
;       for (int j = 0; j < 4; ++j) {
;         const int n = nt * 128 + wn * 64 + j * 16 + (lane >> 4) * 4;
;         uint2 o;
;         o.x = pack2(outv[i][j][0], outv[i][j][1]);
;         o.y = pack2(outv[i][j][2], outv[i][j][3]);
;         *(uint2*)(MG + (size_t)m * 1024 + n) = o;
;       }
;     }
	v_add3_u32 v14, v88, v11, s37
	v_and_b32_sdwa v11, v87, v183 dst_sel:DWORD dst_unused:UNUSED_PAD src0_sel:WORD_1 src1_sel:DWORD
	v_and_b32_sdwa v15, v86, v183 dst_sel:DWORD dst_unused:UNUSED_PAD src0_sel:WORD_1 src1_sel:DWORD
	v_and_b32_sdwa v10, v89, v183 dst_sel:DWORD dst_unused:UNUSED_PAD src0_sel:WORD_1 src1_sel:DWORD
	v_add3_u32 v11, v87, v11, s37
	v_add3_u32 v15, v86, v15, s37
	v_add3_u32 v10, v89, v10, s37
	v_and_b32_e32 v11, 0xffff0000, v11
	v_and_b32_e32 v15, 0xffff0000, v15
	v_or_b32_sdwa v11, v11, v10 dst_sel:DWORD dst_unused:UNUSED_PAD src0_sel:DWORD src1_sel:WORD_1
	v_or_b32_sdwa v10, v15, v14 dst_sel:DWORD dst_unused:UNUSED_PAD src0_sel:DWORD src1_sel:WORD_1
	global_store_dwordx2 v[4:5], v[10:11], off offset:64
	v_and_b32_sdwa v11, v84, v183 dst_sel:DWORD dst_unused:UNUSED_PAD src0_sel:WORD_1 src1_sel:DWORD
	v_add3_u32 v14, v84, v11, s37
	v_and_b32_sdwa v11, v83, v183 dst_sel:DWORD dst_unused:UNUSED_PAD src0_sel:WORD_1 src1_sel:DWORD
	v_and_b32_sdwa v15, v82, v183 dst_sel:DWORD dst_unused:UNUSED_PAD src0_sel:WORD_1 src1_sel:DWORD
	v_and_b32_sdwa v10, v85, v183 dst_sel:DWORD dst_unused:UNUSED_PAD src0_sel:WORD_1 src1_sel:DWORD
	v_add3_u32 v11, v83, v11, s37
	v_add3_u32 v15, v82, v15, s37
	v_add3_u32 v10, v85, v10, s37
	v_and_b32_e32 v11, 0xffff0000, v11
	v_and_b32_e32 v15, 0xffff0000, v15
	v_or_b32_sdwa v11, v11, v10 dst_sel:DWORD dst_unused:UNUSED_PAD src0_sel:DWORD src1_sel:WORD_1
	v_or_b32_sdwa v10, v15, v14 dst_sel:DWORD dst_unused:UNUSED_PAD src0_sel:DWORD src1_sel:WORD_1
	v_ashrrev_i32_e32 v13, 31, v12
	global_store_dwordx2 v[4:5], v[10:11], off offset:96
	v_and_b32_sdwa v11, v80, v183 dst_sel:DWORD dst_unused:UNUSED_PAD src0_sel:WORD_1 src1_sel:DWORD
	v_lshlrev_b64 v[4:5], 11, v[12:13]
	v_add3_u32 v12, v80, v11, s37
	v_and_b32_sdwa v11, v79, v183 dst_sel:DWORD dst_unused:UNUSED_PAD src0_sel:WORD_1 src1_sel:DWORD
	v_and_b32_sdwa v13, v78, v183 dst_sel:DWORD dst_unused:UNUSED_PAD src0_sel:WORD_1 src1_sel:DWORD
	v_and_b32_sdwa v10, v81, v183 dst_sel:DWORD dst_unused:UNUSED_PAD src0_sel:WORD_1 src1_sel:DWORD
	v_add3_u32 v11, v79, v11, s37
	v_add3_u32 v13, v78, v13, s37
	v_lshl_add_u64 v[4:5], s[12:13], 0, v[4:5]
	v_add3_u32 v10, v81, v10, s37
	v_and_b32_e32 v11, 0xffff0000, v11
	v_and_b32_e32 v13, 0xffff0000, v13
	v_lshl_add_u64 v[4:5], v[4:5], 0, v[6:7]
	v_or_b32_sdwa v11, v11, v10 dst_sel:DWORD dst_unused:UNUSED_PAD src0_sel:DWORD src1_sel:WORD_1
	v_or_b32_sdwa v10, v13, v12 dst_sel:DWORD dst_unused:UNUSED_PAD src0_sel:DWORD src1_sel:WORD_1
	global_store_dwordx2 v[4:5], v[10:11], off
	v_and_b32_sdwa v11, v76, v183 dst_sel:DWORD dst_unused:UNUSED_PAD src0_sel:WORD_1 src1_sel:DWORD
	v_add3_u32 v12, v76, v11, s37
	v_and_b32_sdwa v11, v75, v183 dst_sel:DWORD dst_unused:UNUSED_PAD src0_sel:WORD_1 src1_sel:DWORD
	v_and_b32_sdwa v13, v74, v183 dst_sel:DWORD dst_unused:UNUSED_PAD src0_sel:WORD_1 src1_sel:DWORD
	v_and_b32_sdwa v10, v77, v183 dst_sel:DWORD dst_unused:UNUSED_PAD src0_sel:WORD_1 src1_sel:DWORD
	v_add3_u32 v11, v75, v11, s37
	v_add3_u32 v13, v74, v13, s37
	v_add3_u32 v10, v77, v10, s37
	v_and_b32_e32 v11, 0xffff0000, v11
	v_and_b32_e32 v13, 0xffff0000, v13
	v_or_b32_sdwa v11, v11, v10 dst_sel:DWORD dst_unused:UNUSED_PAD src0_sel:DWORD src1_sel:WORD_1
	v_or_b32_sdwa v10, v13, v12 dst_sel:DWORD dst_unused:UNUSED_PAD src0_sel:DWORD src1_sel:WORD_1
	global_store_dwordx2 v[4:5], v[10:11], off offset:32
	v_and_b32_sdwa v11, v72, v183 dst_sel:DWORD dst_unused:UNUSED_PAD src0_sel:WORD_1 src1_sel:DWORD
	v_add3_u32 v12, v72, v11, s37
	v_and_b32_sdwa v11, v71, v183 dst_sel:DWORD dst_unused:UNUSED_PAD src0_sel:WORD_1 src1_sel:DWORD
	v_and_b32_sdwa v13, v70, v183 dst_sel:DWORD dst_unused:UNUSED_PAD src0_sel:WORD_1 src1_sel:DWORD
	v_and_b32_sdwa v10, v73, v183 dst_sel:DWORD dst_unused:UNUSED_PAD src0_sel:WORD_1 src1_sel:DWORD
	v_add3_u32 v11, v71, v11, s37
	v_add3_u32 v13, v70, v13, s37
	v_add3_u32 v10, v73, v10, s37
	v_and_b32_e32 v11, 0xffff0000, v11
	v_and_b32_e32 v13, 0xffff0000, v13
	v_or_b32_sdwa v11, v11, v10 dst_sel:DWORD dst_unused:UNUSED_PAD src0_sel:DWORD src1_sel:WORD_1
	v_or_b32_sdwa v10, v13, v12 dst_sel:DWORD dst_unused:UNUSED_PAD src0_sel:DWORD src1_sel:WORD_1
	global_store_dwordx2 v[4:5], v[10:11], off offset:64
	v_and_b32_sdwa v11, v68, v183 dst_sel:DWORD dst_unused:UNUSED_PAD src0_sel:WORD_1 src1_sel:DWORD
; __device__ __forceinline__ unsigned pack2(float a, float b) { return (unsigned)f2bf(a) | ((unsigned)f2bf(b) << 16); }
; __device__ __forceinline__ void phase_gemm_merge(const Params& p, char* smem) {
;     ...
; #pragma unroll
;     for (int i = 0; i < 4; ++i) {
;       const int m = mt * 128 + wm * 64 + i * 16 + (lane & 15);
; #pragma unroll
;       for (int j = 0; j < 4; ++j) {
;         const int n = nt * 128 + wn * 64 + j * 16 + (lane >> 4) * 4;
;         uint2 o;
;         o.x = pack2(outv[i][j][0], outv[i][j][1]);
;         o.y = pack2(outv[i][j][2], outv[i][j][3]);
;         *(uint2*)(MG + (size_t)m * 1024 + n) = o;
;       }
;     }
	v_add3_u32 v12, v68, v11, s37
	v_and_b32_sdwa v11, v67, v183 dst_sel:DWORD dst_unused:UNUSED_PAD src0_sel:WORD_1 src1_sel:DWORD
	v_and_b32_sdwa v13, v66, v183 dst_sel:DWORD dst_unused:UNUSED_PAD src0_sel:WORD_1 src1_sel:DWORD
	v_and_b32_sdwa v10, v69, v183 dst_sel:DWORD dst_unused:UNUSED_PAD src0_sel:WORD_1 src1_sel:DWORD
	v_add3_u32 v11, v67, v11, s37
	v_add3_u32 v13, v66, v13, s37
	v_add3_u32 v10, v69, v10, s37
	v_and_b32_e32 v11, 0xffff0000, v11
	v_and_b32_e32 v13, 0xffff0000, v13
	v_ashrrev_i32_e32 v9, 31, v8
	v_or_b32_sdwa v11, v11, v10 dst_sel:DWORD dst_unused:UNUSED_PAD src0_sel:DWORD src1_sel:WORD_1
	v_or_b32_sdwa v10, v13, v12 dst_sel:DWORD dst_unused:UNUSED_PAD src0_sel:DWORD src1_sel:WORD_1
	global_store_dwordx2 v[4:5], v[10:11], off offset:96
	v_lshlrev_b64 v[4:5], 11, v[8:9]
	v_lshl_add_u64 v[4:5], s[12:13], 0, v[4:5]
	v_lshl_add_u64 v[4:5], v[4:5], 0, v[6:7]
	v_and_b32_sdwa v7, v64, v183 dst_sel:DWORD dst_unused:UNUSED_PAD src0_sel:WORD_1 src1_sel:DWORD
	v_add3_u32 v8, v64, v7, s37
	v_and_b32_sdwa v7, v63, v183 dst_sel:DWORD dst_unused:UNUSED_PAD src0_sel:WORD_1 src1_sel:DWORD
	v_and_b32_sdwa v9, v62, v183 dst_sel:DWORD dst_unused:UNUSED_PAD src0_sel:WORD_1 src1_sel:DWORD
	v_and_b32_sdwa v6, v65, v183 dst_sel:DWORD dst_unused:UNUSED_PAD src0_sel:WORD_1 src1_sel:DWORD
	v_add3_u32 v7, v63, v7, s37
	v_add3_u32 v9, v62, v9, s37
	v_add3_u32 v6, v65, v6, s37
	v_and_b32_e32 v7, 0xffff0000, v7
	v_and_b32_e32 v9, 0xffff0000, v9
	v_or_b32_sdwa v7, v7, v6 dst_sel:DWORD dst_unused:UNUSED_PAD src0_sel:DWORD src1_sel:WORD_1
	v_or_b32_sdwa v6, v9, v8 dst_sel:DWORD dst_unused:UNUSED_PAD src0_sel:DWORD src1_sel:WORD_1
	global_store_dwordx2 v[4:5], v[6:7], off
	v_and_b32_sdwa v7, v60, v183 dst_sel:DWORD dst_unused:UNUSED_PAD src0_sel:WORD_1 src1_sel:DWORD
	v_add3_u32 v8, v60, v7, s37
	v_and_b32_sdwa v7, v59, v183 dst_sel:DWORD dst_unused:UNUSED_PAD src0_sel:WORD_1 src1_sel:DWORD
	v_and_b32_sdwa v9, v58, v183 dst_sel:DWORD dst_unused:UNUSED_PAD src0_sel:WORD_1 src1_sel:DWORD
	v_and_b32_sdwa v6, v61, v183 dst_sel:DWORD dst_unused:UNUSED_PAD src0_sel:WORD_1 src1_sel:DWORD
	v_add3_u32 v7, v59, v7, s37
	v_add3_u32 v9, v58, v9, s37
	v_add3_u32 v6, v61, v6, s37
	v_and_b32_e32 v7, 0xffff0000, v7
	v_and_b32_e32 v9, 0xffff0000, v9
	v_or_b32_sdwa v7, v7, v6 dst_sel:DWORD dst_unused:UNUSED_PAD src0_sel:DWORD src1_sel:WORD_1
	v_or_b32_sdwa v6, v9, v8 dst_sel:DWORD dst_unused:UNUSED_PAD src0_sel:DWORD src1_sel:WORD_1
	global_store_dwordx2 v[4:5], v[6:7], off offset:32
	v_and_b32_sdwa v7, v56, v183 dst_sel:DWORD dst_unused:UNUSED_PAD src0_sel:WORD_1 src1_sel:DWORD
	v_add3_u32 v8, v56, v7, s37
	v_and_b32_sdwa v7, v55, v183 dst_sel:DWORD dst_unused:UNUSED_PAD src0_sel:WORD_1 src1_sel:DWORD
	v_and_b32_sdwa v9, v54, v183 dst_sel:DWORD dst_unused:UNUSED_PAD src0_sel:WORD_1 src1_sel:DWORD
	v_and_b32_sdwa v6, v57, v183 dst_sel:DWORD dst_unused:UNUSED_PAD src0_sel:WORD_1 src1_sel:DWORD
	v_add3_u32 v7, v55, v7, s37
	v_add3_u32 v9, v54, v9, s37
	v_add3_u32 v6, v57, v6, s37
	v_and_b32_e32 v7, 0xffff0000, v7
	v_and_b32_e32 v9, 0xffff0000, v9
	v_or_b32_sdwa v7, v7, v6 dst_sel:DWORD dst_unused:UNUSED_PAD src0_sel:DWORD src1_sel:WORD_1
	v_or_b32_sdwa v6, v9, v8 dst_sel:DWORD dst_unused:UNUSED_PAD src0_sel:DWORD src1_sel:WORD_1
	global_store_dwordx2 v[4:5], v[6:7], off offset:64
	v_and_b32_sdwa v6, v1, v183 dst_sel:DWORD dst_unused:UNUSED_PAD src0_sel:WORD_1 src1_sel:DWORD
	v_and_b32_sdwa v7, v0, v183 dst_sel:DWORD dst_unused:UNUSED_PAD src0_sel:WORD_1 src1_sel:DWORD
	v_add3_u32 v0, v0, v7, s37
	v_add3_u32 v1, v1, v6, s37
	v_and_b32_sdwa v6, v53, v183 dst_sel:DWORD dst_unused:UNUSED_PAD src0_sel:WORD_1 src1_sel:DWORD
	v_and_b32_sdwa v7, v52, v183 dst_sel:DWORD dst_unused:UNUSED_PAD src0_sel:WORD_1 src1_sel:DWORD
	v_add3_u32 v6, v53, v6, s37
	v_add3_u32 v7, v52, v7, s37
	s_add_i32 s24, s24, 1
	v_and_b32_e32 v6, 0xffff0000, v6
	v_and_b32_e32 v7, 0xffff0000, v7
	s_cmp_eq_u32 s24, s22
	v_or_b32_sdwa v1, v6, v1 dst_sel:DWORD dst_unused:UNUSED_PAD src0_sel:DWORD src1_sel:WORD_1
	v_or_b32_sdwa v0, v7, v0 dst_sel:DWORD dst_unused:UNUSED_PAD src0_sel:DWORD src1_sel:WORD_1
	s_cselect_b64 s[12:13], -1, 0
	s_mov_b32 s31, 0x18000
	global_store_dwordx2 v[4:5], v[0:1], off offset:96
	s_branch .LBB0_18
